# nt also on last-use loads: prologue weights, M1/XN in the row passes, XB/ZB in the RG-LRU phase, Q and gate loads in attention
# baseline (speedup 1.0000x reference)
.LBB0_29:
	s_lshl_b32 s44, s42, 1
	s_lshl_b32 s45, s7, 1
	v_add_u32_e32 v56, s44, v24
	v_add_u32_e32 v54, s45, v21
	v_add_u32_e32 v58, s45, v25
	v_add_u32_e32 v60, s44, v28
	v_add_u32_e32 v90, s45, v29
	v_add_u32_e32 v92, s44, v32
	v_add_u32_e32 v98, s45, v33
	v_add_u32_e32 v100, s44, v36
	v_add_u32_e32 v102, s45, v37
	v_add_u32_e32 v104, s44, v40
	v_add_u32_e32 v106, s45, v41
	v_add_u32_e32 v108, s44, v44
	v_add_u32_e32 v110, s45, v45
	v_add_u32_e32 v112, s44, v48
	v_add_u32_e32 v114, s45, v49
	v_add_u32_e32 v116, s44, v52
	v_ashrrev_i32_e32 v57, 31, v56
	v_ashrrev_i32_e32 v55, 31, v54
	v_ashrrev_i32_e32 v61, 31, v60
	v_ashrrev_i32_e32 v59, 31, v58
	v_ashrrev_i32_e32 v93, 31, v92
	v_ashrrev_i32_e32 v91, 31, v90
	v_ashrrev_i32_e32 v101, 31, v100
	v_ashrrev_i32_e32 v99, 31, v98
	v_ashrrev_i32_e32 v105, 31, v104
	v_ashrrev_i32_e32 v103, 31, v102
	v_ashrrev_i32_e32 v109, 31, v108
	v_ashrrev_i32_e32 v107, 31, v106
	v_ashrrev_i32_e32 v113, 31, v112
	v_ashrrev_i32_e32 v111, 31, v110
	v_ashrrev_i32_e32 v117, 31, v116
	v_ashrrev_i32_e32 v115, 31, v114
	v_lshlrev_b64 v[56:57], 12, v[56:57]
	v_lshlrev_b64 v[54:55], 12, v[54:55]
	v_lshlrev_b64 v[58:59], 12, v[58:59]
	v_lshlrev_b64 v[60:61], 12, v[60:61]
	v_lshlrev_b64 v[90:91], 12, v[90:91]
	v_lshlrev_b64 v[92:93], 12, v[92:93]
	v_lshlrev_b64 v[98:99], 12, v[98:99]
	v_lshlrev_b64 v[100:101], 12, v[100:101]
	v_lshlrev_b64 v[102:103], 12, v[102:103]
	v_lshlrev_b64 v[104:105], 12, v[104:105]
	v_lshlrev_b64 v[106:107], 12, v[106:107]
	v_lshlrev_b64 v[108:109], 12, v[108:109]
	v_lshlrev_b64 v[110:111], 12, v[110:111]
	v_lshlrev_b64 v[112:113], 12, v[112:113]
	v_lshlrev_b64 v[114:115], 12, v[114:115]
	v_lshlrev_b64 v[116:117], 12, v[116:117]
	v_lshl_add_u64 v[56:57], v[18:19], 0, v[56:57]
	v_lshl_add_u64 v[54:55], v[18:19], 0, v[54:55]
	v_lshl_add_u64 v[60:61], v[18:19], 0, v[60:61]
	v_lshl_add_u64 v[58:59], v[18:19], 0, v[58:59]
	v_lshl_add_u64 v[92:93], v[18:19], 0, v[92:93]
	v_lshl_add_u64 v[90:91], v[18:19], 0, v[90:91]
	v_lshl_add_u64 v[100:101], v[18:19], 0, v[100:101]
	v_lshl_add_u64 v[98:99], v[18:19], 0, v[98:99]
	v_lshl_add_u64 v[104:105], v[18:19], 0, v[104:105]
	v_lshl_add_u64 v[102:103], v[18:19], 0, v[102:103]
	v_lshl_add_u64 v[108:109], v[18:19], 0, v[108:109]
	v_lshl_add_u64 v[106:107], v[18:19], 0, v[106:107]
	v_lshl_add_u64 v[112:113], v[18:19], 0, v[112:113]
	v_lshl_add_u64 v[110:111], v[18:19], 0, v[110:111]
	v_lshl_add_u64 v[116:117], v[18:19], 0, v[116:117]
	v_lshl_add_u64 v[114:115], v[18:19], 0, v[114:115]
	global_load_dword v51, v[56:57], off nt
	global_load_dword v53, v[54:55], off nt
	global_load_dword v62, v[60:61], off nt
	global_load_dword v82, v[58:59], off nt
	global_load_dword v86, v[92:93], off nt
	global_load_dword v89, v[90:91], off nt
	global_load_dword v118, v[100:101], off nt
	global_load_dword v119, v[98:99], off nt
	global_load_dword v120, v[104:105], off nt
	global_load_dword v121, v[102:103], off nt
	global_load_dword v122, v[108:109], off nt
	global_load_dword v123, v[106:107], off nt
	global_load_dword v124, v[112:113], off nt
	global_load_dword v125, v[110:111], off nt
	global_load_dword v126, v[116:117], off nt
	global_load_dword v127, v[114:115], off nt
	s_add_i32 s42, s42, 16
	s_add_i32 s7, s7, 16
	s_add_i32 s43, s43, -16
	v_add_u32_e32 v54, s44, v22
	v_add_u32_e32 v56, s45, v1
	v_add_u32_e32 v60, s45, v23
	v_add_u32_e32 v58, s44, v26
	v_add_u32_e32 v92, s45, v27
	v_add_u32_e32 v90, s44, v30
	v_add_u32_e32 v100, s45, v31
	v_add_u32_e32 v98, s44, v34
	v_add_u32_e32 v104, s45, v35
	v_add_u32_e32 v102, s44, v38
	v_add_u32_e32 v108, s45, v39
	v_add_u32_e32 v106, s44, v42
	v_add_u32_e32 v112, s45, v43
	v_add_u32_e32 v110, s44, v46
	v_add_u32_e32 v116, s45, v47
	v_add_u32_e32 v114, s44, v50
	s_cmp_lg_u32 s43, 0
	v_mad_u64_u32 v[54:55], s[44:45], v54, s63, v[20:21]
	v_mad_u64_u32 v[56:57], s[44:45], v56, s63, v[20:21]
	v_mad_u64_u32 v[58:59], s[44:45], v58, s63, v[20:21]
	v_mad_u64_u32 v[60:61], s[44:45], v60, s63, v[20:21]
	v_mad_u64_u32 v[90:91], s[44:45], v90, s63, v[20:21]
	v_mad_u64_u32 v[92:93], s[44:45], v92, s63, v[20:21]
	v_mad_u64_u32 v[98:99], s[44:45], v98, s63, v[20:21]
	v_mad_u64_u32 v[100:101], s[44:45], v100, s63, v[20:21]
	v_mad_u64_u32 v[102:103], s[44:45], v102, s63, v[20:21]
	v_mad_u64_u32 v[104:105], s[44:45], v104, s63, v[20:21]
	v_mad_u64_u32 v[106:107], s[44:45], v106, s63, v[20:21]
	v_mad_u64_u32 v[108:109], s[44:45], v108, s63, v[20:21]
	v_mad_u64_u32 v[110:111], s[44:45], v110, s63, v[20:21]
	v_mad_u64_u32 v[112:113], s[44:45], v112, s63, v[20:21]
	v_mad_u64_u32 v[114:115], s[44:45], v114, s63, v[20:21]
	v_mad_u64_u32 v[116:117], s[44:45], v116, s63, v[20:21]
	s_waitcnt vmcnt(15)
	ds_write_b32 v54, v51
	s_waitcnt vmcnt(14)
	ds_write_b32 v56, v53
	s_waitcnt vmcnt(13)
	ds_write_b32 v58, v62
	s_waitcnt vmcnt(12)
	ds_write_b32 v60, v82
	s_waitcnt vmcnt(11)
	ds_write_b32 v90, v86
	s_waitcnt vmcnt(10)
	ds_write_b32 v92, v89
	s_waitcnt vmcnt(9)
	ds_write_b32 v98, v118
	s_waitcnt vmcnt(8)
	ds_write_b32 v100, v119
	s_waitcnt vmcnt(7)
	ds_write_b32 v102, v120
	s_waitcnt vmcnt(6)
	ds_write_b32 v104, v121
	s_waitcnt vmcnt(5)
	ds_write_b32 v106, v122
	s_waitcnt vmcnt(4)
	ds_write_b32 v108, v123
	s_waitcnt vmcnt(3)
	ds_write_b32 v110, v124
	s_waitcnt vmcnt(2)
	ds_write_b32 v112, v125
	s_waitcnt vmcnt(1)
	ds_write_b32 v114, v126
	s_waitcnt vmcnt(0)
	ds_write_b32 v116, v127
	s_cbranch_scc1 .LBB0_29
	v_lshlrev_b32_e32 v18, 3, v88
	v_ashrrev_i32_e32 v1, 3, v88
	v_and_b32_e32 v20, 56, v18
	s_waitcnt lgkmcnt(0)
	v_mul_u32_u24_e32 v18, 0x84, v20
	v_lshlrev_b32_e32 v19, 2, v1
	v_add3_u32 v30, s62, v18, v19
	s_and_b32 s6, 0xffff, s6
	ds_read2_b32 v[18:19], v30 offset1:33
	s_and_b32 s10, 0xffff, s10
	s_lshl_b32 s6, s6, 1
	s_add_u32 s6, s4, s6
	s_addc_u32 s7, s5, 0
	v_lshlrev_b32_e32 v62, 1, v20
	v_lshl_add_u64 v[20:21], s[6:7], 0, v[62:63]
	v_lshl_add_u64 v[22:23], v[20:21], 0, s[16:17]
	s_waitcnt lgkmcnt(0)
	v_bfe_u32 v20, v18, 16, 1
	v_add3_u32 v18, v18, v20, s64
	ds_read2_b32 v[20:21], v30 offset0:66 offset1:99
	v_bfe_u32 v24, v19, 16, 1
	v_add3_u32 v19, v19, v24, s64
	ds_read2_b32 v[24:25], v30 offset0:132 offset1:165
	v_lshrrev_b32_e32 v18, 16, v18
	v_and_or_b32 v18, v19, s66, v18
	s_waitcnt lgkmcnt(1)
	v_bfe_u32 v19, v20, 16, 1
	v_add3_u32 v19, v20, v19, s64
	v_bfe_u32 v20, v21, 16, 1
	ds_read2_b32 v[26:27], v30 offset0:198 offset1:231
	v_lshrrev_b32_e32 v19, 16, v19
	v_add3_u32 v20, v21, v20, s64
	v_and_or_b32 v19, v20, s66, v19
	s_waitcnt lgkmcnt(1)
	v_bfe_u32 v20, v24, 16, 1
	v_add3_u32 v20, v24, v20, s64
	v_bfe_u32 v21, v25, 16, 1
	v_lshrrev_b32_e32 v20, 16, v20
	v_add3_u32 v21, v25, v21, s64
	v_and_or_b32 v20, v21, s66, v20
	s_waitcnt lgkmcnt(0)
	v_bfe_u32 v21, v26, 16, 1
	v_add3_u32 v21, v26, v21, s64
	v_bfe_u32 v24, v27, 16, 1
	v_lshrrev_b32_e32 v21, 16, v21
	v_add3_u32 v24, v27, v24, s64
	v_and_or_b32 v21, v24, s66, v21
	v_add_u32_e32 v24, s10, v1
	v_ashrrev_i32_e32 v25, 31, v24
	v_lshlrev_b64 v[26:27], 11, v[24:25]
	v_lshl_add_u64 v[26:27], v[22:23], 0, v[26:27]
	global_store_dwordx4 v[26:27], v[18:21], off sc0 sc1
	s_nop 1
	ds_read2_b32 v[18:19], v30 offset0:8 offset1:41
	ds_read2_b32 v[20:21], v30 offset0:74 offset1:107
	ds_read2_b32 v[26:27], v30 offset0:140 offset1:173
	ds_read2_b32 v[28:29], v30 offset0:206 offset1:239
	v_readfirstlane_b32 s10, v97
	s_waitcnt lgkmcnt(3)
	v_bfe_u32 v1, v18, 16, 1
	v_add3_u32 v1, v18, v1, s64
	v_bfe_u32 v18, v19, 16, 1
	v_lshrrev_b32_e32 v1, 16, v1
	v_add3_u32 v18, v19, v18, s64
	v_and_or_b32 v18, v18, s66, v1
	s_waitcnt lgkmcnt(2)
	v_bfe_u32 v1, v20, 16, 1
	v_add3_u32 v1, v20, v1, s64
	v_bfe_u32 v19, v21, 16, 1
	v_lshrrev_b32_e32 v1, 16, v1
	v_add3_u32 v19, v21, v19, s64
	v_and_or_b32 v19, v19, s66, v1
	s_waitcnt lgkmcnt(1)
	v_bfe_u32 v1, v26, 16, 1
	v_add3_u32 v1, v26, v1, s64
	v_bfe_u32 v20, v27, 16, 1
	v_lshrrev_b32_e32 v1, 16, v1
	v_add3_u32 v20, v27, v20, s64
	v_and_or_b32 v20, v20, s66, v1
	s_waitcnt lgkmcnt(0)
	v_bfe_u32 v1, v28, 16, 1
	v_add_u32_e32 v26, 8, v24
	v_add3_u32 v1, v28, v1, s64
	v_bfe_u32 v21, v29, 16, 1
	v_ashrrev_i32_e32 v27, 31, v26
	v_lshrrev_b32_e32 v1, 16, v1
	v_add3_u32 v21, v29, v21, s64
	v_lshlrev_b64 v[26:27], 11, v[26:27]
	v_and_or_b32 v21, v21, s66, v1
	v_lshl_add_u64 v[26:27], v[22:23], 0, v[26:27]
	global_store_dwordx4 v[26:27], v[18:21], off sc0 sc1
	s_nop 1
	ds_read2_b32 v[18:19], v30 offset0:16 offset1:49
	ds_read2_b32 v[20:21], v30 offset0:82 offset1:115
	ds_read2_b32 v[26:27], v30 offset0:148 offset1:181
	ds_read2_b32 v[28:29], v30 offset0:214 offset1:247
	s_mov_b64 s[6:7], 0
	s_waitcnt lgkmcnt(3)
	v_bfe_u32 v1, v18, 16, 1
	v_add3_u32 v1, v18, v1, s64
	v_bfe_u32 v18, v19, 16, 1
	v_lshrrev_b32_e32 v1, 16, v1
	v_add3_u32 v18, v19, v18, s64
	v_and_or_b32 v18, v18, s66, v1
	s_waitcnt lgkmcnt(2)
	v_bfe_u32 v1, v20, 16, 1
	v_add3_u32 v1, v20, v1, s64
	v_bfe_u32 v19, v21, 16, 1
	v_lshrrev_b32_e32 v1, 16, v1
	v_add3_u32 v19, v21, v19, s64
	v_and_or_b32 v19, v19, s66, v1
	s_waitcnt lgkmcnt(1)
	v_bfe_u32 v1, v26, 16, 1
	v_add3_u32 v1, v26, v1, s64
	v_bfe_u32 v20, v27, 16, 1
	v_lshrrev_b32_e32 v1, 16, v1
	v_add3_u32 v20, v27, v20, s64
	v_and_or_b32 v20, v20, s66, v1
	s_waitcnt lgkmcnt(0)
	v_bfe_u32 v1, v28, 16, 1
	v_add_u32_e32 v26, 16, v24
	v_add3_u32 v1, v28, v1, s64
	v_bfe_u32 v21, v29, 16, 1
	v_ashrrev_i32_e32 v27, 31, v26
	v_lshrrev_b32_e32 v1, 16, v1
	v_add3_u32 v21, v29, v21, s64
	v_lshlrev_b64 v[26:27], 11, v[26:27]
	v_and_or_b32 v21, v21, s66, v1
	v_lshl_add_u64 v[26:27], v[22:23], 0, v[26:27]
	global_store_dwordx4 v[26:27], v[18:21], off sc0 sc1
	s_nop 1
	ds_read2_b32 v[18:19], v30 offset0:24 offset1:57
	ds_read2_b32 v[20:21], v30 offset0:90 offset1:123
	ds_read2_b32 v[26:27], v30 offset0:156 offset1:189
	ds_read2_b32 v[28:29], v30 offset0:222 offset1:255
	v_add_u32_e32 v24, 24, v24
	s_waitcnt lgkmcnt(3)
	v_bfe_u32 v1, v18, 16, 1
	v_add3_u32 v1, v18, v1, s64
	v_bfe_u32 v18, v19, 16, 1
	v_lshrrev_b32_e32 v1, 16, v1
	v_add3_u32 v18, v19, v18, s64
	v_and_or_b32 v18, v18, s66, v1
	s_waitcnt lgkmcnt(2)
	v_bfe_u32 v1, v20, 16, 1
	v_add3_u32 v1, v20, v1, s64
	v_bfe_u32 v19, v21, 16, 1
	v_lshrrev_b32_e32 v1, 16, v1
	v_add3_u32 v19, v21, v19, s64
	v_and_or_b32 v19, v19, s66, v1
	s_waitcnt lgkmcnt(1)
	v_bfe_u32 v1, v26, 16, 1
	v_add3_u32 v1, v26, v1, s64
	v_bfe_u32 v20, v27, 16, 1
	v_lshrrev_b32_e32 v1, 16, v1
	v_add3_u32 v20, v27, v20, s64
	v_and_or_b32 v20, v20, s66, v1
	s_waitcnt lgkmcnt(0)
	v_bfe_u32 v1, v28, 16, 1
	v_add3_u32 v1, v28, v1, s64
	v_bfe_u32 v21, v29, 16, 1
	v_ashrrev_i32_e32 v25, 31, v24
	v_lshrrev_b32_e32 v1, 16, v1
	v_add3_u32 v21, v29, v21, s64
	v_lshlrev_b64 v[24:25], 11, v[24:25]
	v_and_or_b32 v21, v21, s66, v1
	v_lshl_add_u64 v[22:23], v[22:23], 0, v[24:25]
	global_store_dwordx4 v[22:23], v[18:21], off sc0 sc1
	s_nop 1
	s_waitcnt lgkmcnt(0)

.LBB0_33:
	s_lshl_b32 s44, s42, 1
	s_lshl_b32 s45, s10, 1
	v_add_u32_e32 v54, s45, v21
	v_add_u32_e32 v56, s44, v24
	v_add_u32_e32 v58, s45, v25
	v_add_u32_e32 v60, s44, v28
	v_add_u32_e32 v90, s45, v29
	v_add_u32_e32 v92, s44, v32
	v_add_u32_e32 v98, s45, v33
	v_add_u32_e32 v100, s44, v36
	v_add_u32_e32 v102, s45, v37
	v_add_u32_e32 v104, s44, v40
	v_add_u32_e32 v106, s45, v41
	v_add_u32_e32 v108, s44, v44
	v_add_u32_e32 v110, s45, v45
	v_add_u32_e32 v112, s44, v48
	v_add_u32_e32 v116, s44, v52
	v_add_u32_e32 v114, s45, v49
	v_ashrrev_i32_e32 v57, 31, v56
	v_ashrrev_i32_e32 v55, 31, v54
	v_ashrrev_i32_e32 v61, 31, v60
	v_ashrrev_i32_e32 v59, 31, v58
	v_ashrrev_i32_e32 v93, 31, v92
	v_ashrrev_i32_e32 v91, 31, v90
	v_ashrrev_i32_e32 v101, 31, v100
	v_ashrrev_i32_e32 v99, 31, v98
	v_ashrrev_i32_e32 v105, 31, v104
	v_ashrrev_i32_e32 v103, 31, v102
	v_ashrrev_i32_e32 v109, 31, v108
	v_ashrrev_i32_e32 v107, 31, v106
	v_ashrrev_i32_e32 v113, 31, v112
	v_ashrrev_i32_e32 v111, 31, v110
	v_ashrrev_i32_e32 v117, 31, v116
	v_ashrrev_i32_e32 v115, 31, v114
	v_lshlrev_b64 v[118:119], 13, v[54:55]
	v_lshlrev_b64 v[120:121], 13, v[56:57]
	v_lshl_add_u64 v[56:57], v[56:57], 2, s[14:15]
	v_lshl_add_u64 v[54:55], v[54:55], 2, s[14:15]
	v_lshlrev_b64 v[122:123], 13, v[58:59]
	v_lshlrev_b64 v[124:125], 13, v[60:61]
	v_lshl_add_u64 v[60:61], v[60:61], 2, s[14:15]
	v_lshl_add_u64 v[58:59], v[58:59], 2, s[14:15]
	v_lshlrev_b64 v[126:127], 13, v[90:91]
	v_lshlrev_b64 v[128:129], 13, v[92:93]
	v_lshl_add_u64 v[92:93], v[92:93], 2, s[14:15]
	v_lshl_add_u64 v[90:91], v[90:91], 2, s[14:15]
	v_lshlrev_b64 v[130:131], 13, v[98:99]
	v_lshlrev_b64 v[132:133], 13, v[100:101]
	v_lshl_add_u64 v[100:101], v[100:101], 2, s[14:15]
	v_lshl_add_u64 v[98:99], v[98:99], 2, s[14:15]
	v_lshlrev_b64 v[134:135], 13, v[102:103]
	v_lshlrev_b64 v[136:137], 13, v[104:105]
	v_lshl_add_u64 v[104:105], v[104:105], 2, s[14:15]
	v_lshl_add_u64 v[102:103], v[102:103], 2, s[14:15]
	v_lshlrev_b64 v[138:139], 13, v[106:107]
	v_lshlrev_b64 v[140:141], 13, v[108:109]
	v_lshl_add_u64 v[108:109], v[108:109], 2, s[14:15]
	v_lshl_add_u64 v[106:107], v[106:107], 2, s[14:15]
	v_lshlrev_b64 v[142:143], 13, v[110:111]
	v_lshlrev_b64 v[144:145], 13, v[112:113]
	v_lshl_add_u64 v[112:113], v[112:113], 2, s[14:15]
	v_lshl_add_u64 v[110:111], v[110:111], 2, s[14:15]
	v_lshlrev_b64 v[148:149], 13, v[116:117]
	v_lshlrev_b64 v[146:147], 13, v[114:115]
	v_lshl_add_u64 v[116:117], v[116:117], 2, s[14:15]
	v_lshl_add_u64 v[114:115], v[114:115], 2, s[14:15]
	global_load_dword v56, v[56:57], off nt
	s_nop 0
	global_load_dword v57, v[54:55], off nt
	v_lshl_add_u64 v[54:55], v[18:19], 0, v[124:125]
	global_load_dword v60, v[60:61], off nt
	s_nop 0
	global_load_dword v61, v[58:59], off nt
	v_lshl_add_u64 v[58:59], v[18:19], 0, v[128:129]
	global_load_dword v92, v[92:93], off nt
	s_nop 0
	global_load_dword v93, v[90:91], off nt
	v_lshl_add_u64 v[90:91], v[18:19], 0, v[132:133]
	global_load_dword v100, v[100:101], off nt
	s_nop 0
	global_load_dword v101, v[98:99], off nt
	v_lshl_add_u64 v[98:99], v[18:19], 0, v[136:137]
	global_load_dword v104, v[104:105], off nt
	s_nop 0
	global_load_dword v105, v[102:103], off nt
	v_lshl_add_u64 v[102:103], v[18:19], 0, v[140:141]
	global_load_dword v108, v[108:109], off nt
	s_nop 0
	global_load_dword v109, v[106:107], off nt
	v_lshl_add_u64 v[106:107], v[18:19], 0, v[144:145]
	global_load_dword v112, v[112:113], off nt
	s_nop 0
	global_load_dword v113, v[110:111], off nt
	v_lshl_add_u64 v[110:111], v[18:19], 0, v[148:149]
	v_lshl_add_u64 v[120:121], v[18:19], 0, v[120:121]
	v_lshl_add_u64 v[118:119], v[18:19], 0, v[118:119]
	v_lshl_add_u64 v[122:123], v[18:19], 0, v[122:123]
	v_lshl_add_u64 v[124:125], v[18:19], 0, v[126:127]
	v_lshl_add_u64 v[126:127], v[18:19], 0, v[130:131]
	v_lshl_add_u64 v[128:129], v[18:19], 0, v[134:135]
	v_lshl_add_u64 v[130:131], v[18:19], 0, v[138:139]
	v_lshl_add_u64 v[132:133], v[18:19], 0, v[142:143]
	v_lshl_add_u64 v[134:135], v[18:19], 0, v[146:147]
	global_load_dword v116, v[116:117], off nt
	s_nop 0
	global_load_dword v117, v[114:115], off nt
	s_nop 0
	global_load_dword v114, v[120:121], off nt
	global_load_dword v115, v[118:119], off nt
	s_nop 0
	global_load_dword v54, v[54:55], off nt
	s_nop 0
	global_load_dword v55, v[122:123], off nt
	s_nop 0
	global_load_dword v58, v[58:59], off nt
	s_nop 0
	global_load_dword v59, v[124:125], off nt
	s_nop 0
	global_load_dword v90, v[90:91], off nt
	s_nop 0
	global_load_dword v91, v[126:127], off nt
	s_nop 0
	global_load_dword v98, v[98:99], off nt
	s_nop 0
	global_load_dword v99, v[128:129], off nt
	s_nop 0
	global_load_dword v102, v[102:103], off nt
	s_nop 0
	global_load_dword v103, v[130:131], off nt
	s_nop 0
	global_load_dword v106, v[106:107], off nt
	s_nop 0
	global_load_dword v107, v[132:133], off nt
	s_nop 0
	global_load_dword v110, v[110:111], off nt
	s_nop 0
	global_load_dword v111, v[134:135], off nt
	s_add_i32 s42, s42, 16
	s_add_i32 s10, s10, 16
	s_add_i32 s43, s43, -16
	v_add_u32_e32 v53, s44, v22
	v_add_u32_e32 v51, s45, v1
	v_add_u32_e32 v62, s45, v23
	v_add_u32_e32 v82, s44, v26
	v_add_u32_e32 v86, s45, v27
	v_add_u32_e32 v89, s44, v30
	v_add_u32_e32 v132, s45, v31
	v_add_u32_e32 v130, s44, v34
	v_add_u32_e32 v136, s45, v35
	v_add_u32_e32 v134, s44, v38
	v_add_u32_e32 v140, s45, v39
	v_add_u32_e32 v138, s44, v42
	v_add_u32_e32 v144, s45, v43
	v_add_u32_e32 v142, s44, v46
	v_add_u32_e32 v148, s45, v47
	v_add_u32_e32 v146, s44, v50
	s_cmp_lg_u32 s43, 0
	v_mad_u64_u32 v[118:119], s[44:45], v53, s63, v[20:21]
	v_mad_u64_u32 v[120:121], s[44:45], v51, s63, v[20:21]
	v_mad_u64_u32 v[122:123], s[44:45], v82, s63, v[20:21]
	v_mad_u64_u32 v[124:125], s[44:45], v62, s63, v[20:21]
	v_mad_u64_u32 v[126:127], s[44:45], v89, s63, v[20:21]
	v_mad_u64_u32 v[128:129], s[44:45], v86, s63, v[20:21]
	v_mad_u64_u32 v[130:131], s[44:45], v130, s63, v[20:21]
	v_mad_u64_u32 v[132:133], s[44:45], v132, s63, v[20:21]
	v_mad_u64_u32 v[134:135], s[44:45], v134, s63, v[20:21]
	v_mad_u64_u32 v[136:137], s[44:45], v136, s63, v[20:21]
	v_mad_u64_u32 v[138:139], s[44:45], v138, s63, v[20:21]
	v_mad_u64_u32 v[140:141], s[44:45], v140, s63, v[20:21]
	v_mad_u64_u32 v[142:143], s[44:45], v142, s63, v[20:21]
	v_mad_u64_u32 v[144:145], s[44:45], v144, s63, v[20:21]
	v_mad_u64_u32 v[146:147], s[44:45], v146, s63, v[20:21]
	v_mad_u64_u32 v[148:149], s[44:45], v148, s63, v[20:21]
	s_waitcnt vmcnt(14)
	v_pk_mul_f32 v[56:57], v[114:115], v[56:57]
	s_waitcnt vmcnt(12)
	v_pk_mul_f32 v[54:55], v[54:55], v[60:61]
	s_waitcnt vmcnt(10)
	v_pk_mul_f32 v[58:59], v[58:59], v[92:93]
	s_waitcnt vmcnt(8)
	v_pk_mul_f32 v[60:61], v[90:91], v[100:101]
	s_waitcnt vmcnt(6)
	v_pk_mul_f32 v[90:91], v[98:99], v[104:105]
	s_waitcnt vmcnt(4)
	v_pk_mul_f32 v[92:93], v[102:103], v[108:109]
	s_waitcnt vmcnt(2)
	v_pk_mul_f32 v[98:99], v[106:107], v[112:113]
	s_waitcnt vmcnt(0)
	v_pk_mul_f32 v[100:101], v[110:111], v[116:117]
	ds_write_b32 v118, v56
	ds_write_b32 v120, v57
	ds_write_b32 v122, v54
	ds_write_b32 v124, v55
	ds_write_b32 v126, v58
	ds_write_b32 v128, v59
	ds_write_b32 v130, v60
	ds_write_b32 v132, v61
	ds_write_b32 v134, v90
	ds_write_b32 v136, v91
	ds_write_b32 v138, v92
	ds_write_b32 v140, v93
	ds_write_b32 v142, v98
	ds_write_b32 v144, v99
	ds_write_b32 v146, v100
	ds_write_b32 v148, v101
	s_cbranch_scc1 .LBB0_33
	v_lshlrev_b32_e32 v18, 3, v88
	v_ashrrev_i32_e32 v1, 3, v88
	v_and_b32_e32 v20, 56, v18
	s_waitcnt lgkmcnt(0)
	v_mul_u32_u24_e32 v18, 0x84, v20
	v_lshlrev_b32_e32 v19, 2, v1
	v_add3_u32 v30, s62, v18, v19
	s_and_b32 s6, 0xffff, s6
	ds_read2_b32 v[18:19], v30 offset1:33
	s_and_b32 s7, 0xffff, s7
	s_lshl_b32 s6, s6, 1
	s_add_u32 s4, s4, s6
	s_addc_u32 s5, s5, 0
	v_lshlrev_b32_e32 v62, 1, v20
	v_lshl_add_u64 v[20:21], s[4:5], 0, v[62:63]
	v_lshl_add_u64 v[22:23], v[20:21], 0, s[18:19]
	s_waitcnt lgkmcnt(0)
	v_bfe_u32 v20, v18, 16, 1
	v_add3_u32 v18, v18, v20, s64
	ds_read2_b32 v[20:21], v30 offset0:66 offset1:99
	v_bfe_u32 v24, v19, 16, 1
	v_add3_u32 v19, v19, v24, s64
	ds_read2_b32 v[24:25], v30 offset0:132 offset1:165
	v_lshrrev_b32_e32 v18, 16, v18
	v_and_or_b32 v18, v19, s66, v18
	s_waitcnt lgkmcnt(1)
	v_bfe_u32 v19, v20, 16, 1
	v_add3_u32 v19, v20, v19, s64
	v_bfe_u32 v20, v21, 16, 1
	ds_read2_b32 v[26:27], v30 offset0:198 offset1:231
	v_lshrrev_b32_e32 v19, 16, v19
	v_add3_u32 v20, v21, v20, s64
	v_and_or_b32 v19, v20, s66, v19
	s_waitcnt lgkmcnt(1)
	v_bfe_u32 v20, v24, 16, 1
	v_add3_u32 v20, v24, v20, s64
	v_bfe_u32 v21, v25, 16, 1
	v_lshrrev_b32_e32 v20, 16, v20
	v_add3_u32 v21, v25, v21, s64
	v_and_or_b32 v20, v21, s66, v20
	s_waitcnt lgkmcnt(0)
	v_bfe_u32 v21, v26, 16, 1
	v_add3_u32 v21, v26, v21, s64
	v_bfe_u32 v24, v27, 16, 1
	v_lshrrev_b32_e32 v21, 16, v21
	v_add3_u32 v24, v27, v24, s64
	v_and_or_b32 v21, v24, s66, v21
	v_add_u32_e32 v24, s7, v1
	v_ashrrev_i32_e32 v25, 31, v24
	v_lshlrev_b64 v[26:27], 11, v[24:25]
	v_lshl_add_u64 v[26:27], v[22:23], 0, v[26:27]
	global_store_dwordx4 v[26:27], v[18:21], off sc0 sc1
	s_nop 1
	ds_read2_b32 v[18:19], v30 offset0:8 offset1:41
	ds_read2_b32 v[20:21], v30 offset0:74 offset1:107
	ds_read2_b32 v[26:27], v30 offset0:140 offset1:173
	ds_read2_b32 v[28:29], v30 offset0:206 offset1:239
	v_readfirstlane_b32 s10, v97
	s_waitcnt lgkmcnt(3)
	v_bfe_u32 v1, v18, 16, 1
	v_add3_u32 v1, v18, v1, s64
	v_bfe_u32 v18, v19, 16, 1
	v_lshrrev_b32_e32 v1, 16, v1
	v_add3_u32 v18, v19, v18, s64
	v_and_or_b32 v18, v18, s66, v1
	s_waitcnt lgkmcnt(2)
	v_bfe_u32 v1, v20, 16, 1
	v_add3_u32 v1, v20, v1, s64
	v_bfe_u32 v19, v21, 16, 1
	v_lshrrev_b32_e32 v1, 16, v1
	v_add3_u32 v19, v21, v19, s64
	v_and_or_b32 v19, v19, s66, v1
	s_waitcnt lgkmcnt(1)
	v_bfe_u32 v1, v26, 16, 1
	v_add3_u32 v1, v26, v1, s64
	v_bfe_u32 v20, v27, 16, 1
	v_lshrrev_b32_e32 v1, 16, v1
	v_add3_u32 v20, v27, v20, s64
	v_and_or_b32 v20, v20, s66, v1
	s_waitcnt lgkmcnt(0)
	v_bfe_u32 v1, v28, 16, 1
	v_add_u32_e32 v26, 8, v24
	v_add3_u32 v1, v28, v1, s64
	v_bfe_u32 v21, v29, 16, 1
	v_ashrrev_i32_e32 v27, 31, v26
	v_lshrrev_b32_e32 v1, 16, v1
	v_add3_u32 v21, v29, v21, s64
	v_lshlrev_b64 v[26:27], 11, v[26:27]
	v_and_or_b32 v21, v21, s66, v1
	v_lshl_add_u64 v[26:27], v[22:23], 0, v[26:27]
	global_store_dwordx4 v[26:27], v[18:21], off sc0 sc1
	s_nop 1
	ds_read2_b32 v[18:19], v30 offset0:16 offset1:49
	ds_read2_b32 v[20:21], v30 offset0:82 offset1:115
	ds_read2_b32 v[26:27], v30 offset0:148 offset1:181
	ds_read2_b32 v[28:29], v30 offset0:214 offset1:247
	s_waitcnt lgkmcnt(3)
	v_bfe_u32 v1, v18, 16, 1
	v_add3_u32 v1, v18, v1, s64
	v_bfe_u32 v18, v19, 16, 1
	v_lshrrev_b32_e32 v1, 16, v1
	v_add3_u32 v18, v19, v18, s64
	v_and_or_b32 v18, v18, s66, v1
	s_waitcnt lgkmcnt(2)
	v_bfe_u32 v1, v20, 16, 1
	v_add3_u32 v1, v20, v1, s64
	v_bfe_u32 v19, v21, 16, 1
	v_lshrrev_b32_e32 v1, 16, v1
	v_add3_u32 v19, v21, v19, s64
	v_and_or_b32 v19, v19, s66, v1
	s_waitcnt lgkmcnt(1)
	v_bfe_u32 v1, v26, 16, 1
	v_add3_u32 v1, v26, v1, s64
	v_bfe_u32 v20, v27, 16, 1
	v_lshrrev_b32_e32 v1, 16, v1
	v_add3_u32 v20, v27, v20, s64
	v_and_or_b32 v20, v20, s66, v1
	s_waitcnt lgkmcnt(0)
	v_bfe_u32 v1, v28, 16, 1
	v_add_u32_e32 v26, 16, v24
	v_add3_u32 v1, v28, v1, s64
	v_bfe_u32 v21, v29, 16, 1
	v_ashrrev_i32_e32 v27, 31, v26
	v_lshrrev_b32_e32 v1, 16, v1
	v_add3_u32 v21, v29, v21, s64
	v_lshlrev_b64 v[26:27], 11, v[26:27]
	v_and_or_b32 v21, v21, s66, v1
	v_lshl_add_u64 v[26:27], v[22:23], 0, v[26:27]
	global_store_dwordx4 v[26:27], v[18:21], off sc0 sc1
	s_nop 1
	ds_read2_b32 v[18:19], v30 offset0:24 offset1:57
	ds_read2_b32 v[20:21], v30 offset0:90 offset1:123
	ds_read2_b32 v[26:27], v30 offset0:156 offset1:189
	ds_read2_b32 v[28:29], v30 offset0:222 offset1:255
	v_add_u32_e32 v24, 24, v24
	s_waitcnt lgkmcnt(3)
	v_bfe_u32 v1, v18, 16, 1
	v_add3_u32 v1, v18, v1, s64
	v_bfe_u32 v18, v19, 16, 1
	v_lshrrev_b32_e32 v1, 16, v1
	v_add3_u32 v18, v19, v18, s64
	v_and_or_b32 v18, v18, s66, v1
	s_waitcnt lgkmcnt(2)
	v_bfe_u32 v1, v20, 16, 1
	v_add3_u32 v1, v20, v1, s64
	v_bfe_u32 v19, v21, 16, 1
	v_lshrrev_b32_e32 v1, 16, v1
	v_add3_u32 v19, v21, v19, s64
	v_and_or_b32 v19, v19, s66, v1
	s_waitcnt lgkmcnt(1)
	v_bfe_u32 v1, v26, 16, 1
	v_add3_u32 v1, v26, v1, s64
	v_bfe_u32 v20, v27, 16, 1
	v_lshrrev_b32_e32 v1, 16, v1
	v_add3_u32 v20, v27, v20, s64
	v_and_or_b32 v20, v20, s66, v1
	s_waitcnt lgkmcnt(0)
	v_bfe_u32 v1, v28, 16, 1
	v_add3_u32 v1, v28, v1, s64
	v_bfe_u32 v21, v29, 16, 1
	v_ashrrev_i32_e32 v25, 31, v24
	v_lshrrev_b32_e32 v1, 16, v1
	v_add3_u32 v21, v29, v21, s64
	v_lshlrev_b64 v[24:25], 11, v[24:25]
	v_and_or_b32 v21, v21, s66, v1
	v_lshl_add_u64 v[22:23], v[22:23], 0, v[24:25]
	global_store_dwordx4 v[22:23], v[18:21], off sc0 sc1
	s_nop 1
	s_waitcnt lgkmcnt(0)

.LBB0_38:
	s_lshl_b32 s44, s42, 1
	s_lshl_b32 s45, s7, 1
	v_add_u32_e32 v56, s44, v24
	v_add_u32_e32 v54, s45, v21
	v_add_u32_e32 v58, s45, v25
	v_add_u32_e32 v60, s44, v28
	v_add_u32_e32 v90, s45, v29
	v_add_u32_e32 v92, s44, v32
	v_add_u32_e32 v98, s45, v33
	v_add_u32_e32 v100, s44, v36
	v_add_u32_e32 v102, s45, v37
	v_add_u32_e32 v104, s44, v40
	v_add_u32_e32 v106, s45, v41
	v_add_u32_e32 v108, s44, v44
	v_add_u32_e32 v110, s45, v45
	v_add_u32_e32 v112, s44, v48
	v_add_u32_e32 v114, s45, v49
	v_add_u32_e32 v116, s44, v52
	v_ashrrev_i32_e32 v57, 31, v56
	v_ashrrev_i32_e32 v55, 31, v54
	v_ashrrev_i32_e32 v61, 31, v60
	v_ashrrev_i32_e32 v59, 31, v58
	v_ashrrev_i32_e32 v93, 31, v92
	v_ashrrev_i32_e32 v91, 31, v90
	v_ashrrev_i32_e32 v101, 31, v100
	v_ashrrev_i32_e32 v99, 31, v98
	v_ashrrev_i32_e32 v105, 31, v104
	v_ashrrev_i32_e32 v103, 31, v102
	v_ashrrev_i32_e32 v109, 31, v108
	v_ashrrev_i32_e32 v107, 31, v106
	v_ashrrev_i32_e32 v113, 31, v112
	v_ashrrev_i32_e32 v111, 31, v110
	v_ashrrev_i32_e32 v117, 31, v116
	v_ashrrev_i32_e32 v115, 31, v114
	v_lshlrev_b64 v[56:57], 12, v[56:57]
	v_lshlrev_b64 v[54:55], 12, v[54:55]
	v_lshlrev_b64 v[58:59], 12, v[58:59]
	v_lshlrev_b64 v[60:61], 12, v[60:61]
	v_lshlrev_b64 v[90:91], 12, v[90:91]
	v_lshlrev_b64 v[92:93], 12, v[92:93]
	v_lshlrev_b64 v[98:99], 12, v[98:99]
	v_lshlrev_b64 v[100:101], 12, v[100:101]
	v_lshlrev_b64 v[102:103], 12, v[102:103]
	v_lshlrev_b64 v[104:105], 12, v[104:105]
	v_lshlrev_b64 v[106:107], 12, v[106:107]
	v_lshlrev_b64 v[108:109], 12, v[108:109]
	v_lshlrev_b64 v[110:111], 12, v[110:111]
	v_lshlrev_b64 v[112:113], 12, v[112:113]
	v_lshlrev_b64 v[114:115], 12, v[114:115]
	v_lshlrev_b64 v[116:117], 12, v[116:117]
	v_lshl_add_u64 v[56:57], v[18:19], 0, v[56:57]
	v_lshl_add_u64 v[54:55], v[18:19], 0, v[54:55]
	v_lshl_add_u64 v[60:61], v[18:19], 0, v[60:61]
	v_lshl_add_u64 v[58:59], v[18:19], 0, v[58:59]
	v_lshl_add_u64 v[92:93], v[18:19], 0, v[92:93]
	v_lshl_add_u64 v[90:91], v[18:19], 0, v[90:91]
	v_lshl_add_u64 v[100:101], v[18:19], 0, v[100:101]
	v_lshl_add_u64 v[98:99], v[18:19], 0, v[98:99]
	v_lshl_add_u64 v[104:105], v[18:19], 0, v[104:105]
	v_lshl_add_u64 v[102:103], v[18:19], 0, v[102:103]
	v_lshl_add_u64 v[108:109], v[18:19], 0, v[108:109]
	v_lshl_add_u64 v[106:107], v[18:19], 0, v[106:107]
	v_lshl_add_u64 v[112:113], v[18:19], 0, v[112:113]
	v_lshl_add_u64 v[110:111], v[18:19], 0, v[110:111]
	v_lshl_add_u64 v[116:117], v[18:19], 0, v[116:117]
	v_lshl_add_u64 v[114:115], v[18:19], 0, v[114:115]
	global_load_dword v51, v[56:57], off nt
	global_load_dword v53, v[54:55], off nt
	global_load_dword v62, v[60:61], off nt
	global_load_dword v82, v[58:59], off nt
	global_load_dword v86, v[92:93], off nt
	global_load_dword v89, v[90:91], off nt
	global_load_dword v118, v[100:101], off nt
	global_load_dword v119, v[98:99], off nt
	global_load_dword v120, v[104:105], off nt
	global_load_dword v121, v[102:103], off nt
	global_load_dword v122, v[108:109], off nt
	global_load_dword v123, v[106:107], off nt
	global_load_dword v124, v[112:113], off nt
	global_load_dword v125, v[110:111], off nt
	global_load_dword v126, v[116:117], off nt
	global_load_dword v127, v[114:115], off nt
	s_add_i32 s42, s42, 16
	s_add_i32 s7, s7, 16
	s_add_i32 s43, s43, -16
	v_add_u32_e32 v54, s44, v22
	v_add_u32_e32 v56, s45, v1
	v_add_u32_e32 v60, s45, v23
	v_add_u32_e32 v58, s44, v26
	v_add_u32_e32 v92, s45, v27
	v_add_u32_e32 v90, s44, v30
	v_add_u32_e32 v100, s45, v31
	v_add_u32_e32 v98, s44, v34
	v_add_u32_e32 v104, s45, v35
	v_add_u32_e32 v102, s44, v38
	v_add_u32_e32 v108, s45, v39
	v_add_u32_e32 v106, s44, v42
	v_add_u32_e32 v112, s45, v43
	v_add_u32_e32 v110, s44, v46
	v_add_u32_e32 v116, s45, v47
	v_add_u32_e32 v114, s44, v50
	s_cmp_lg_u32 s43, 0
	v_mad_u64_u32 v[54:55], s[44:45], v54, s63, v[20:21]
	v_mad_u64_u32 v[56:57], s[44:45], v56, s63, v[20:21]
	v_mad_u64_u32 v[58:59], s[44:45], v58, s63, v[20:21]
	v_mad_u64_u32 v[60:61], s[44:45], v60, s63, v[20:21]
	v_mad_u64_u32 v[90:91], s[44:45], v90, s63, v[20:21]
	v_mad_u64_u32 v[92:93], s[44:45], v92, s63, v[20:21]
	v_mad_u64_u32 v[98:99], s[44:45], v98, s63, v[20:21]
	v_mad_u64_u32 v[100:101], s[44:45], v100, s63, v[20:21]
	v_mad_u64_u32 v[102:103], s[44:45], v102, s63, v[20:21]
	v_mad_u64_u32 v[104:105], s[44:45], v104, s63, v[20:21]
	v_mad_u64_u32 v[106:107], s[44:45], v106, s63, v[20:21]
	v_mad_u64_u32 v[108:109], s[44:45], v108, s63, v[20:21]
	v_mad_u64_u32 v[110:111], s[44:45], v110, s63, v[20:21]
	v_mad_u64_u32 v[112:113], s[44:45], v112, s63, v[20:21]
	v_mad_u64_u32 v[114:115], s[44:45], v114, s63, v[20:21]
	v_mad_u64_u32 v[116:117], s[44:45], v116, s63, v[20:21]
	s_waitcnt vmcnt(15)
	ds_write_b32 v54, v51
	s_waitcnt vmcnt(14)
	ds_write_b32 v56, v53
	s_waitcnt vmcnt(13)
	ds_write_b32 v58, v62
	s_waitcnt vmcnt(12)
	ds_write_b32 v60, v82
	s_waitcnt vmcnt(11)
	ds_write_b32 v90, v86
	s_waitcnt vmcnt(10)
	ds_write_b32 v92, v89
	s_waitcnt vmcnt(9)
	ds_write_b32 v98, v118
	s_waitcnt vmcnt(8)
	ds_write_b32 v100, v119
	s_waitcnt vmcnt(7)
	ds_write_b32 v102, v120
	s_waitcnt vmcnt(6)
	ds_write_b32 v104, v121
	s_waitcnt vmcnt(5)
	ds_write_b32 v106, v122
	s_waitcnt vmcnt(4)
	ds_write_b32 v108, v123
	s_waitcnt vmcnt(3)
	ds_write_b32 v110, v124
	s_waitcnt vmcnt(2)
	ds_write_b32 v112, v125
	s_waitcnt vmcnt(1)
	ds_write_b32 v114, v126
	s_waitcnt vmcnt(0)
	ds_write_b32 v116, v127
	s_cbranch_scc1 .LBB0_38
	v_lshlrev_b32_e32 v18, 3, v88
	v_ashrrev_i32_e32 v1, 3, v88
	v_and_b32_e32 v20, 56, v18
	s_waitcnt lgkmcnt(0)
	v_mul_u32_u24_e32 v18, 0x84, v20
	v_lshlrev_b32_e32 v19, 2, v1
	v_add3_u32 v30, s62, v18, v19
	s_and_b32 s6, 0xffff, s6
	ds_read2_b32 v[18:19], v30 offset1:33
	s_and_b32 s7, 0xffff, s10
	s_lshl_b32 s6, s6, 1
	s_add_u32 s4, s4, s6
	s_addc_u32 s5, s5, 0
	v_lshlrev_b32_e32 v62, 1, v20
	v_lshl_add_u64 v[20:21], s[4:5], 0, v[62:63]
	v_lshl_add_u64 v[22:23], v[20:21], 0, s[20:21]
	s_waitcnt lgkmcnt(0)
	v_bfe_u32 v20, v18, 16, 1
	v_add3_u32 v18, v18, v20, s64
	ds_read2_b32 v[20:21], v30 offset0:66 offset1:99
	v_bfe_u32 v24, v19, 16, 1
	v_add3_u32 v19, v19, v24, s64
	ds_read2_b32 v[24:25], v30 offset0:132 offset1:165
	v_lshrrev_b32_e32 v18, 16, v18
	v_and_or_b32 v18, v19, s66, v18
	s_waitcnt lgkmcnt(1)
	v_bfe_u32 v19, v20, 16, 1
	v_add3_u32 v19, v20, v19, s64
	v_bfe_u32 v20, v21, 16, 1
	ds_read2_b32 v[26:27], v30 offset0:198 offset1:231
	v_lshrrev_b32_e32 v19, 16, v19
	v_add3_u32 v20, v21, v20, s64
	v_and_or_b32 v19, v20, s66, v19
	s_waitcnt lgkmcnt(1)
	v_bfe_u32 v20, v24, 16, 1
	v_add3_u32 v20, v24, v20, s64
	v_bfe_u32 v21, v25, 16, 1
	v_lshrrev_b32_e32 v20, 16, v20
	v_add3_u32 v21, v25, v21, s64
	v_and_or_b32 v20, v21, s66, v20
	s_waitcnt lgkmcnt(0)
	v_bfe_u32 v21, v26, 16, 1
	v_add3_u32 v21, v26, v21, s64
	v_bfe_u32 v24, v27, 16, 1
	v_lshrrev_b32_e32 v21, 16, v21
	v_add3_u32 v24, v27, v24, s64
	v_and_or_b32 v21, v24, s66, v21
	v_add_u32_e32 v24, s7, v1
	v_ashrrev_i32_e32 v25, 31, v24
	v_lshlrev_b64 v[26:27], 11, v[24:25]
	v_lshl_add_u64 v[26:27], v[22:23], 0, v[26:27]
	global_store_dwordx4 v[26:27], v[18:21], off sc0 sc1
	s_nop 1
	ds_read2_b32 v[18:19], v30 offset0:8 offset1:41
	ds_read2_b32 v[20:21], v30 offset0:74 offset1:107
	ds_read2_b32 v[26:27], v30 offset0:140 offset1:173
	ds_read2_b32 v[28:29], v30 offset0:206 offset1:239
	v_readfirstlane_b32 s10, v97
	s_waitcnt lgkmcnt(3)
	v_bfe_u32 v1, v18, 16, 1
	v_add3_u32 v1, v18, v1, s64
	v_bfe_u32 v18, v19, 16, 1
	v_lshrrev_b32_e32 v1, 16, v1
	v_add3_u32 v18, v19, v18, s64
	v_and_or_b32 v18, v18, s66, v1
	s_waitcnt lgkmcnt(2)
	v_bfe_u32 v1, v20, 16, 1
	v_add3_u32 v1, v20, v1, s64
	v_bfe_u32 v19, v21, 16, 1
	v_lshrrev_b32_e32 v1, 16, v1
	v_add3_u32 v19, v21, v19, s64
	v_and_or_b32 v19, v19, s66, v1
	s_waitcnt lgkmcnt(1)
	v_bfe_u32 v1, v26, 16, 1
	v_add3_u32 v1, v26, v1, s64
	v_bfe_u32 v20, v27, 16, 1
	v_lshrrev_b32_e32 v1, 16, v1
	v_add3_u32 v20, v27, v20, s64
	v_and_or_b32 v20, v20, s66, v1
	s_waitcnt lgkmcnt(0)
	v_bfe_u32 v1, v28, 16, 1
	v_add_u32_e32 v26, 8, v24
	v_add3_u32 v1, v28, v1, s64
	v_bfe_u32 v21, v29, 16, 1
	v_ashrrev_i32_e32 v27, 31, v26
	v_lshrrev_b32_e32 v1, 16, v1
	v_add3_u32 v21, v29, v21, s64
	v_lshlrev_b64 v[26:27], 11, v[26:27]
	v_and_or_b32 v21, v21, s66, v1
	v_lshl_add_u64 v[26:27], v[22:23], 0, v[26:27]
	global_store_dwordx4 v[26:27], v[18:21], off sc0 sc1
	s_nop 1
	ds_read2_b32 v[18:19], v30 offset0:16 offset1:49
	ds_read2_b32 v[20:21], v30 offset0:82 offset1:115
	ds_read2_b32 v[26:27], v30 offset0:148 offset1:181
	ds_read2_b32 v[28:29], v30 offset0:214 offset1:247
	s_waitcnt lgkmcnt(3)
	v_bfe_u32 v1, v18, 16, 1
	v_add3_u32 v1, v18, v1, s64
	v_bfe_u32 v18, v19, 16, 1
	v_lshrrev_b32_e32 v1, 16, v1
	v_add3_u32 v18, v19, v18, s64
	v_and_or_b32 v18, v18, s66, v1
	s_waitcnt lgkmcnt(2)
	v_bfe_u32 v1, v20, 16, 1
	v_add3_u32 v1, v20, v1, s64
	v_bfe_u32 v19, v21, 16, 1
	v_lshrrev_b32_e32 v1, 16, v1
	v_add3_u32 v19, v21, v19, s64
	v_and_or_b32 v19, v19, s66, v1
	s_waitcnt lgkmcnt(1)
	v_bfe_u32 v1, v26, 16, 1
	v_add3_u32 v1, v26, v1, s64
	v_bfe_u32 v20, v27, 16, 1
	v_lshrrev_b32_e32 v1, 16, v1
	v_add3_u32 v20, v27, v20, s64
	v_and_or_b32 v20, v20, s66, v1
	s_waitcnt lgkmcnt(0)
	v_bfe_u32 v1, v28, 16, 1
	v_add_u32_e32 v26, 16, v24
	v_add3_u32 v1, v28, v1, s64
	v_bfe_u32 v21, v29, 16, 1
	v_ashrrev_i32_e32 v27, 31, v26
	v_lshrrev_b32_e32 v1, 16, v1
	v_add3_u32 v21, v29, v21, s64
	v_lshlrev_b64 v[26:27], 11, v[26:27]
	v_and_or_b32 v21, v21, s66, v1
	v_lshl_add_u64 v[26:27], v[22:23], 0, v[26:27]
	global_store_dwordx4 v[26:27], v[18:21], off sc0 sc1
	s_nop 1
	ds_read2_b32 v[18:19], v30 offset0:24 offset1:57
	ds_read2_b32 v[20:21], v30 offset0:90 offset1:123
	ds_read2_b32 v[26:27], v30 offset0:156 offset1:189
	ds_read2_b32 v[28:29], v30 offset0:222 offset1:255
	v_add_u32_e32 v24, 24, v24
	s_waitcnt lgkmcnt(3)
	v_bfe_u32 v1, v18, 16, 1
	v_add3_u32 v1, v18, v1, s64
	v_bfe_u32 v18, v19, 16, 1
	v_lshrrev_b32_e32 v1, 16, v1
	v_add3_u32 v18, v19, v18, s64
	v_and_or_b32 v18, v18, s66, v1
	s_waitcnt lgkmcnt(2)
	v_bfe_u32 v1, v20, 16, 1
	v_add3_u32 v1, v20, v1, s64
	v_bfe_u32 v19, v21, 16, 1
	v_lshrrev_b32_e32 v1, 16, v1
	v_add3_u32 v19, v21, v19, s64
	v_and_or_b32 v19, v19, s66, v1
	s_waitcnt lgkmcnt(1)
	v_bfe_u32 v1, v26, 16, 1
	v_add3_u32 v1, v26, v1, s64
	v_bfe_u32 v20, v27, 16, 1
	v_lshrrev_b32_e32 v1, 16, v1
	v_add3_u32 v20, v27, v20, s64
	v_and_or_b32 v20, v20, s66, v1
	s_waitcnt lgkmcnt(0)
	v_bfe_u32 v1, v28, 16, 1
	v_add3_u32 v1, v28, v1, s64
	v_bfe_u32 v21, v29, 16, 1
	v_ashrrev_i32_e32 v25, 31, v24
	v_lshrrev_b32_e32 v1, 16, v1
	v_add3_u32 v21, v29, v21, s64
	v_lshlrev_b64 v[24:25], 11, v[24:25]
	v_and_or_b32 v21, v21, s66, v1
	v_lshl_add_u64 v[22:23], v[22:23], 0, v[24:25]
	global_store_dwordx4 v[22:23], v[18:21], off sc0 sc1
	s_nop 1
	s_waitcnt lgkmcnt(0)

.LBB0_43:
	s_lshl_b32 s46, s42, 1
	s_lshl_b32 s47, s10, 1
	v_add_u32_e32 v53, s46, v24
	v_add_u32_e32 v51, s47, v21
	v_add_u32_e32 v60, s47, v25
	v_add_u32_e32 v58, s46, v28
	v_add_u32_e32 v62, s47, v29
	v_add_u32_e32 v82, s46, v32
	v_add_u32_e32 v86, s47, v33
	v_add_u32_e32 v89, s46, v36
	v_add_u32_e32 v104, s47, v37
	v_add_u32_e32 v102, s46, v40
	v_add_u32_e32 v108, s47, v41
	v_add_u32_e32 v106, s46, v44
	v_add_u32_e32 v112, s47, v45
	v_add_u32_e32 v110, s46, v48
	v_add_u32_e32 v116, s47, v49
	v_add_u32_e32 v114, s46, v52
	v_mad_i64_i32 v[54:55], s[44:45], v53, s67, v[18:19]
	v_mad_i64_i32 v[56:57], s[44:45], v51, s67, v[18:19]
	v_mad_i64_i32 v[58:59], s[44:45], v58, s67, v[18:19]
	v_mad_i64_i32 v[60:61], s[44:45], v60, s67, v[18:19]
	v_mad_i64_i32 v[90:91], s[44:45], v82, s67, v[18:19]
	v_mad_i64_i32 v[92:93], s[44:45], v62, s67, v[18:19]
	v_mad_i64_i32 v[98:99], s[44:45], v89, s67, v[18:19]
	v_mad_i64_i32 v[100:101], s[44:45], v86, s67, v[18:19]
	v_mad_i64_i32 v[102:103], s[44:45], v102, s67, v[18:19]
	v_mad_i64_i32 v[104:105], s[44:45], v104, s67, v[18:19]
	v_mad_i64_i32 v[106:107], s[44:45], v106, s67, v[18:19]
	v_mad_i64_i32 v[108:109], s[44:45], v108, s67, v[18:19]
	v_mad_i64_i32 v[110:111], s[44:45], v110, s67, v[18:19]
	v_mad_i64_i32 v[112:113], s[44:45], v112, s67, v[18:19]
	v_mad_i64_i32 v[114:115], s[44:45], v114, s67, v[18:19]
	v_mad_i64_i32 v[116:117], s[44:45], v116, s67, v[18:19]
	global_load_dword v51, v[54:55], off nt
	global_load_dword v53, v[56:57], off nt
	global_load_dword v62, v[58:59], off nt
	global_load_dword v82, v[60:61], off nt
	global_load_dword v86, v[90:91], off nt
	global_load_dword v89, v[92:93], off nt
	global_load_dword v118, v[98:99], off nt
	global_load_dword v119, v[100:101], off nt
	global_load_dword v120, v[102:103], off nt
	global_load_dword v121, v[104:105], off nt
	global_load_dword v122, v[106:107], off nt
	global_load_dword v123, v[108:109], off nt
	global_load_dword v124, v[110:111], off nt
	global_load_dword v125, v[112:113], off nt
	global_load_dword v126, v[114:115], off nt
	global_load_dword v127, v[116:117], off nt
	s_add_i32 s42, s42, 16
	s_add_i32 s10, s10, 16
	s_add_i32 s43, s43, -16
	v_add_u32_e32 v54, s46, v22
	v_add_u32_e32 v56, s47, v1
	v_add_u32_e32 v60, s47, v23
	v_add_u32_e32 v58, s46, v26
	v_add_u32_e32 v92, s47, v27
	v_add_u32_e32 v90, s46, v30
	v_add_u32_e32 v100, s47, v31
	v_add_u32_e32 v98, s46, v34
	v_add_u32_e32 v104, s47, v35
	v_add_u32_e32 v102, s46, v38
	v_add_u32_e32 v108, s47, v39
	v_add_u32_e32 v106, s46, v42
	v_add_u32_e32 v112, s47, v43
	v_add_u32_e32 v110, s46, v46
	v_add_u32_e32 v116, s47, v47
	v_add_u32_e32 v114, s46, v50
	s_cmp_lg_u32 s43, 0
	v_mad_u64_u32 v[54:55], s[44:45], v54, s63, v[20:21]
	v_mad_u64_u32 v[56:57], s[44:45], v56, s63, v[20:21]
	v_mad_u64_u32 v[58:59], s[44:45], v58, s63, v[20:21]
	v_mad_u64_u32 v[60:61], s[44:45], v60, s63, v[20:21]
	v_mad_u64_u32 v[90:91], s[44:45], v90, s63, v[20:21]
	v_mad_u64_u32 v[92:93], s[44:45], v92, s63, v[20:21]
	v_mad_u64_u32 v[98:99], s[44:45], v98, s63, v[20:21]
	v_mad_u64_u32 v[100:101], s[44:45], v100, s63, v[20:21]
	v_mad_u64_u32 v[102:103], s[44:45], v102, s63, v[20:21]
	v_mad_u64_u32 v[104:105], s[44:45], v104, s63, v[20:21]
	v_mad_u64_u32 v[106:107], s[44:45], v106, s63, v[20:21]
	v_mad_u64_u32 v[108:109], s[44:45], v108, s63, v[20:21]
	v_mad_u64_u32 v[110:111], s[44:45], v110, s63, v[20:21]
	v_mad_u64_u32 v[112:113], s[44:45], v112, s63, v[20:21]
	v_mad_u64_u32 v[114:115], s[44:45], v114, s63, v[20:21]
	v_mad_u64_u32 v[116:117], s[44:45], v116, s63, v[20:21]
	s_waitcnt vmcnt(15)
	ds_write_b32 v54, v51
	s_waitcnt vmcnt(14)
	ds_write_b32 v56, v53
	s_waitcnt vmcnt(13)
	ds_write_b32 v58, v62
	s_waitcnt vmcnt(12)
	ds_write_b32 v60, v82
	s_waitcnt vmcnt(11)
	ds_write_b32 v90, v86
	s_waitcnt vmcnt(10)
	ds_write_b32 v92, v89
	s_waitcnt vmcnt(9)
	ds_write_b32 v98, v118
	s_waitcnt vmcnt(8)
	ds_write_b32 v100, v119
	s_waitcnt vmcnt(7)
	ds_write_b32 v102, v120
	s_waitcnt vmcnt(6)
	ds_write_b32 v104, v121
	s_waitcnt vmcnt(5)
	ds_write_b32 v106, v122
	s_waitcnt vmcnt(4)
	ds_write_b32 v108, v123
	s_waitcnt vmcnt(3)
	ds_write_b32 v110, v124
	s_waitcnt vmcnt(2)
	ds_write_b32 v112, v125
	s_waitcnt vmcnt(1)
	ds_write_b32 v114, v126
	s_waitcnt vmcnt(0)
	ds_write_b32 v116, v127
	s_cbranch_scc1 .LBB0_43
	v_lshlrev_b32_e32 v18, 3, v88
	v_ashrrev_i32_e32 v1, 3, v88
	v_and_b32_e32 v20, 56, v18
	s_waitcnt lgkmcnt(0)
	v_mul_u32_u24_e32 v18, 0x84, v20
	v_lshlrev_b32_e32 v19, 2, v1
	v_add3_u32 v28, s62, v18, v19
	s_and_b32 s6, 0xffff, s6
	ds_read2_b32 v[18:19], v28 offset1:33
	s_and_b32 s7, 0xffff, s7
	s_lshl_b32 s6, s6, 1
	s_add_u32 s4, s4, s6
	s_addc_u32 s5, s5, 0
	v_lshlrev_b32_e32 v62, 1, v20
	v_lshl_add_u64 v[20:21], s[4:5], 0, v[62:63]
	v_lshl_add_u64 v[22:23], v[20:21], 0, s[24:25]
	s_waitcnt lgkmcnt(0)
	v_bfe_u32 v20, v18, 16, 1
	v_add3_u32 v18, v18, v20, s64
	ds_read2_b32 v[20:21], v28 offset0:66 offset1:99
	v_bfe_u32 v24, v19, 16, 1
	v_add3_u32 v19, v19, v24, s64
	ds_read2_b32 v[24:25], v28 offset0:132 offset1:165
	v_lshrrev_b32_e32 v18, 16, v18
	v_and_or_b32 v18, v19, s66, v18
	s_waitcnt lgkmcnt(1)
	v_bfe_u32 v19, v20, 16, 1
	v_add3_u32 v19, v20, v19, s64
	v_bfe_u32 v20, v21, 16, 1
	ds_read2_b32 v[26:27], v28 offset0:198 offset1:231
	v_lshrrev_b32_e32 v19, 16, v19
	v_add3_u32 v20, v21, v20, s64
	v_and_or_b32 v19, v20, s66, v19
	s_waitcnt lgkmcnt(1)
	v_bfe_u32 v20, v24, 16, 1
	v_add3_u32 v20, v24, v20, s64
	v_bfe_u32 v21, v25, 16, 1
	v_lshrrev_b32_e32 v20, 16, v20
	v_add3_u32 v21, v25, v21, s64
	v_and_or_b32 v20, v21, s66, v20
	s_waitcnt lgkmcnt(0)
	v_bfe_u32 v21, v26, 16, 1
	v_add3_u32 v21, v26, v21, s64
	v_bfe_u32 v24, v27, 16, 1
	v_lshrrev_b32_e32 v21, 16, v21
	v_add3_u32 v24, v27, v24, s64
	v_and_or_b32 v21, v24, s66, v21
	v_add_u32_e32 v24, s7, v1
	v_lshlrev_b32_e32 v25, 1, v1
	v_lshrrev_b32_e32 v26, 3, v24
	v_and_b32_e32 v25, 56, v25
	v_and_b32_e32 v26, 4, v26
	v_and_b32_e32 v27, 0xffffffc3, v24
	v_or3_b32 v25, v27, v25, v26
	v_cmp_gt_i32_e32 vcc, s68, v24
	v_add_u32_e32 v29, 8, v1
	v_readfirstlane_b32 s10, v97
	v_cndmask_b32_e32 v24, v24, v25, vcc
	v_ashrrev_i32_e32 v25, 31, v24
	v_lshlrev_b64 v[24:25], 11, v[24:25]
	v_lshl_add_u64 v[24:25], v[22:23], 0, v[24:25]
	global_store_dwordx4 v[24:25], v[18:21], off sc0 sc1
	s_nop 1
	ds_read2_b32 v[18:19], v28 offset0:8 offset1:41
	ds_read2_b32 v[26:27], v28 offset0:206 offset1:239
	s_waitcnt lgkmcnt(1)
	v_bfe_u32 v20, v18, 16, 1
	v_add3_u32 v18, v18, v20, s64
	ds_read2_b32 v[20:21], v28 offset0:74 offset1:107
	v_bfe_u32 v24, v19, 16, 1
	v_add3_u32 v19, v19, v24, s64
	ds_read2_b32 v[24:25], v28 offset0:140 offset1:173
	v_lshrrev_b32_e32 v18, 16, v18
	v_and_or_b32 v18, v19, s66, v18
	s_waitcnt lgkmcnt(1)
	v_bfe_u32 v19, v20, 16, 1
	v_add3_u32 v19, v20, v19, s64
	v_bfe_u32 v20, v21, 16, 1
	v_lshrrev_b32_e32 v19, 16, v19
	v_add3_u32 v20, v21, v20, s64
	v_and_or_b32 v19, v20, s66, v19
	s_waitcnt lgkmcnt(0)
	v_bfe_u32 v20, v24, 16, 1
	v_add3_u32 v20, v24, v20, s64
	v_bfe_u32 v21, v25, 16, 1
	v_lshrrev_b32_e32 v20, 16, v20
	v_add3_u32 v21, v25, v21, s64
	v_and_or_b32 v20, v21, s66, v20
	v_bfe_u32 v21, v26, 16, 1
	v_add3_u32 v21, v26, v21, s64
	v_bfe_u32 v24, v27, 16, 1
	v_lshrrev_b32_e32 v21, 16, v21
	v_add3_u32 v24, v27, v24, s64
	v_and_or_b32 v21, v24, s66, v21
	v_add_u32_e32 v24, s7, v29
	v_lshlrev_b32_e32 v25, 1, v29
	v_lshrrev_b32_e32 v26, 3, v24
	v_and_b32_e32 v25, 56, v25
	v_and_b32_e32 v26, 4, v26
	v_and_b32_e32 v27, 0xffffffc3, v24
	v_or3_b32 v25, v27, v25, v26
	v_cmp_gt_i32_e32 vcc, s68, v24
	v_add_u32_e32 v29, 16, v1
	v_add_u32_e32 v1, 24, v1
	v_cndmask_b32_e32 v24, v24, v25, vcc
	v_ashrrev_i32_e32 v25, 31, v24
	v_lshlrev_b64 v[24:25], 11, v[24:25]
	v_lshl_add_u64 v[24:25], v[22:23], 0, v[24:25]
	global_store_dwordx4 v[24:25], v[18:21], off sc0 sc1
	s_nop 1
	ds_read2_b32 v[18:19], v28 offset0:16 offset1:49
	ds_read2_b32 v[26:27], v28 offset0:214 offset1:247
	s_waitcnt lgkmcnt(1)
	v_bfe_u32 v20, v18, 16, 1
	v_add3_u32 v18, v18, v20, s64
	ds_read2_b32 v[20:21], v28 offset0:82 offset1:115
	v_bfe_u32 v24, v19, 16, 1
	v_add3_u32 v19, v19, v24, s64
	ds_read2_b32 v[24:25], v28 offset0:148 offset1:181
	v_lshrrev_b32_e32 v18, 16, v18
	v_and_or_b32 v18, v19, s66, v18
	s_waitcnt lgkmcnt(1)
	v_bfe_u32 v19, v20, 16, 1
	v_add3_u32 v19, v20, v19, s64
	v_bfe_u32 v20, v21, 16, 1
	v_lshrrev_b32_e32 v19, 16, v19
	v_add3_u32 v20, v21, v20, s64
	v_and_or_b32 v19, v20, s66, v19
	s_waitcnt lgkmcnt(0)
	v_bfe_u32 v20, v24, 16, 1
	v_add3_u32 v20, v24, v20, s64
	v_bfe_u32 v21, v25, 16, 1
	v_lshrrev_b32_e32 v20, 16, v20
	v_add3_u32 v21, v25, v21, s64
	v_and_or_b32 v20, v21, s66, v20
	v_bfe_u32 v21, v26, 16, 1
	v_add3_u32 v21, v26, v21, s64
	v_bfe_u32 v24, v27, 16, 1
	v_lshrrev_b32_e32 v21, 16, v21
	v_add3_u32 v24, v27, v24, s64
	v_and_or_b32 v21, v24, s66, v21
	v_add_u32_e32 v24, s7, v29
	v_lshlrev_b32_e32 v25, 1, v29
	v_lshrrev_b32_e32 v26, 3, v24
	v_and_b32_e32 v25, 56, v25
	v_and_b32_e32 v26, 4, v26
	v_and_b32_e32 v27, 0xffffffc3, v24
	v_or3_b32 v25, v27, v25, v26
	v_cmp_gt_i32_e32 vcc, s68, v24
	s_nop 1
	v_cndmask_b32_e32 v24, v24, v25, vcc
	v_ashrrev_i32_e32 v25, 31, v24
	v_lshlrev_b64 v[24:25], 11, v[24:25]
	v_lshl_add_u64 v[24:25], v[22:23], 0, v[24:25]
	global_store_dwordx4 v[24:25], v[18:21], off sc0 sc1
	s_nop 1
	ds_read2_b32 v[18:19], v28 offset0:24 offset1:57
	ds_read2_b32 v[26:27], v28 offset0:222 offset1:255
	s_waitcnt lgkmcnt(1)
	v_bfe_u32 v20, v18, 16, 1
	v_add3_u32 v18, v18, v20, s64
	ds_read2_b32 v[20:21], v28 offset0:90 offset1:123
	v_bfe_u32 v24, v19, 16, 1
	v_add3_u32 v19, v19, v24, s64
	ds_read2_b32 v[24:25], v28 offset0:156 offset1:189
	v_lshrrev_b32_e32 v18, 16, v18
	v_and_or_b32 v18, v19, s66, v18
	s_waitcnt lgkmcnt(1)
	v_bfe_u32 v19, v20, 16, 1
	v_add3_u32 v19, v20, v19, s64
	v_bfe_u32 v20, v21, 16, 1
	v_lshrrev_b32_e32 v19, 16, v19
	v_add3_u32 v20, v21, v20, s64
	v_and_or_b32 v19, v20, s66, v19
	s_waitcnt lgkmcnt(0)
	v_bfe_u32 v20, v24, 16, 1
	v_add3_u32 v20, v24, v20, s64
	v_bfe_u32 v21, v25, 16, 1
	v_lshrrev_b32_e32 v20, 16, v20
	v_add3_u32 v21, v25, v21, s64
	v_and_or_b32 v20, v21, s66, v20
	v_bfe_u32 v21, v26, 16, 1
	v_add3_u32 v21, v26, v21, s64
	v_bfe_u32 v24, v27, 16, 1
	v_lshrrev_b32_e32 v21, 16, v21
	v_add3_u32 v24, v27, v24, s64
	v_and_or_b32 v21, v24, s66, v21
	v_add_u32_e32 v24, s7, v1
	v_lshlrev_b32_e32 v1, 1, v1
	v_lshrrev_b32_e32 v25, 3, v24
	v_and_b32_e32 v1, 56, v1
	v_and_b32_e32 v25, 4, v25
	v_and_b32_e32 v26, 0xffffffc3, v24
	v_or3_b32 v1, v26, v1, v25
	v_cmp_gt_i32_e32 vcc, s68, v24
	s_nop 1
	v_cndmask_b32_e32 v24, v24, v1, vcc
	v_ashrrev_i32_e32 v25, 31, v24
	v_lshlrev_b64 v[24:25], 11, v[24:25]
	v_lshl_add_u64 v[22:23], v[22:23], 0, v[24:25]
	global_store_dwordx4 v[22:23], v[18:21], off sc0 sc1
	s_nop 1
	s_waitcnt lgkmcnt(0)

.LBB0_50:
	v_and_b32_e32 v1, 31, v88
	v_lshlrev_b32_e32 v18, 2, v1
	s_getpc_b64 s[4:5]
	s_add_u32 s4, s4, kRopeInv@rel32@lo+4
	s_addc_u32 s5, s5, kRopeInv@rel32@hi+12
	global_load_dword v24, v18, s[4:5] nt
	v_lshl_add_u32 v25, s40, 8, v88
	v_ashrrev_i32_e32 v26, 5, v25
	v_cvt_f32_i32_e32 v18, v26
	s_mov_b32 s40, s38
	v_mov_b32_e32 v82, v70
	s_load_dwordx2 s[6:7], s[8:9], 0xc0
	v_mov_b32_e32 v86, v74
	s_waitcnt vmcnt(0)
	v_mul_f32_e32 v18, v24, v18
	v_cvt_f64_f32_e32 v[18:19], v18
	v_mul_f64 v[20:21], v[18:19], s[28:29]
	v_rndne_f64_e32 v[20:21], v[20:21]
	v_fmac_f64_e32 v[18:19], s[30:31], v[20:21]
	v_fmac_f64_e32 v[18:19], s[36:37], v[20:21]
	v_cvt_i32_f64_e32 v22, v[20:21]
	v_mul_f64 v[20:21], v[18:19], v[18:19]
	v_fma_f64 v[28:29], s[40:41], v[20:21], v[76:77]
	v_and_b32_e32 v27, 3, v22
	v_fma_f64 v[22:23], s[38:39], v[20:21], v[64:65]
	v_fma_f64 v[28:29], v[20:21], v[28:29], v[78:79]
	v_fma_f64 v[22:23], v[20:21], v[22:23], v[66:67]
	v_fma_f64 v[28:29], v[20:21], v[28:29], v[80:81]
	v_fma_f64 v[22:23], v[20:21], v[22:23], v[68:69]
	v_fma_f64 v[28:29], v[20:21], v[28:29], v[82:83]
	v_fma_f64 v[22:23], v[20:21], v[22:23], v[70:71]
	v_fma_f64 v[28:29], v[20:21], v[28:29], v[84:85]
	v_fma_f64 v[22:23], v[20:21], v[22:23], v[72:73]
	v_fma_f64 v[28:29], v[20:21], v[28:29], v[86:87]
	v_fma_f64 v[22:23], v[20:21], v[22:23], v[74:75]
	v_fma_f64 v[28:29], v[20:21], v[28:29], -0.5
	v_fma_f64 v[22:23], v[20:21], v[22:23], 1.0
	v_fma_f64 v[20:21], v[20:21], v[28:29], 1.0
	v_cmp_eq_u32_e32 vcc, 0, v27
	v_mul_f64 v[18:19], v[18:19], v[22:23]
	v_cmp_ne_u32_e64 s[4:5], 0, v27
	v_mov_b64_e32 v[22:23], v[20:21]
	s_and_saveexec_b64 s[42:43], s[4:5]
	s_cbranch_execz .LBB0_54
	v_cmp_ne_u32_e64 s[4:5], 1, v27
	v_xor_b32_e32 v23, 0x80000000, v19
	v_mov_b32_e32 v22, v18
	s_and_saveexec_b64 s[44:45], s[4:5]
	s_xor_b64 s[44:45], exec, s[44:45]
	v_xor_b32_e32 v22, 0x80000000, v21
	v_cmp_eq_u32_e64 s[4:5], 2, v27
	s_nop 1
	v_cndmask_b32_e64 v23, v19, v22, s[4:5]
	v_cndmask_b32_e64 v22, v18, v20, s[4:5]
	s_andn2_saveexec_b64 s[4:5], s[44:45]
	s_or_b64 exec, exec, s[4:5]

.LBB0_499:
	v_lshlrev_b32_e32 v2, 3, v87
	v_lshlrev_b32_e32 v2, 1, v2
	v_lshl_add_u64 v[56:57], s[14:15], 0, v[2:3]
	v_lshl_add_u64 v[64:65], v[56:57], 0, s[18:19]
	v_lshl_add_u64 v[10:11], v[64:65], 0, v[10:11]
	global_load_dwordx4 v[56:59], v[10:11], off nt
	v_lshl_add_u64 v[10:11], v[64:65], 0, v[14:15]
	global_load_dwordx4 v[60:63], v[10:11], off nt
	v_pk_mul_f32 v[10:11], v[36:37], v[54:55] op_sel_hi:[1,0]
	v_pk_mul_f32 v[14:15], v[38:39], v[54:55] op_sel_hi:[1,0]
	v_pk_mul_f32 v[20:21], v[20:21], v[54:55] op_sel_hi:[1,0]
	v_pk_mul_f32 v[22:23], v[22:23], v[54:55] op_sel_hi:[1,0]
	v_cvt_pk_bf16_f32 v10, v10, v11
	v_cvt_pk_bf16_f32 v11, v14, v15
	v_cvt_pk_bf16_f32 v14, v20, v21
	v_lshl_add_u64 v[20:21], v[64:65], 0, v[52:53]
	v_cvt_pk_bf16_f32 v15, v22, v23
	global_load_dwordx4 v[20:23], v[20:21], off nt
	v_pk_mul_f32 v[36:37], v[40:41], v[54:55] op_sel_hi:[1,0]
	v_pk_mul_f32 v[38:39], v[42:43], v[54:55] op_sel_hi:[1,0]
	v_add_u32_e32 v19, 0x1000, v86
	v_pk_mul_f32 v[24:25], v[24:25], v[54:55] op_sel_hi:[1,0]
	v_pk_mul_f32 v[26:27], v[26:27], v[54:55] op_sel_hi:[1,0]
	v_pk_mul_f32 v[40:41], v[44:45], v[54:55] op_sel_hi:[1,0]
	v_pk_mul_f32 v[42:43], v[46:47], v[54:55] op_sel_hi:[1,0]
	v_pk_mul_f32 v[28:29], v[28:29], v[54:55] op_sel_hi:[1,0]
	v_pk_mul_f32 v[30:31], v[30:31], v[54:55] op_sel_hi:[1,0]
	v_pk_mul_f32 v[44:45], v[48:49], v[54:55] op_sel_hi:[1,0]
	v_pk_mul_f32 v[46:47], v[50:51], v[54:55] op_sel_hi:[1,0]
	v_pk_mul_f32 v[32:33], v[32:33], v[54:55] op_sel_hi:[1,0]
	v_pk_mul_f32 v[34:35], v[34:35], v[54:55] op_sel_hi:[1,0]
	v_cvt_pk_bf16_f32 v36, v36, v37
	v_cvt_pk_bf16_f32 v37, v38, v39
	v_cvt_pk_bf16_f32 v24, v24, v25
	v_cvt_pk_bf16_f32 v25, v26, v27
	v_cvt_pk_bf16_f32 v26, v40, v41
	v_cvt_pk_bf16_f32 v27, v42, v43
	v_cvt_pk_bf16_f32 v28, v28, v29
	v_cvt_pk_bf16_f32 v29, v30, v31
	v_cvt_pk_bf16_f32 v30, v44, v45
	v_cvt_pk_bf16_f32 v31, v46, v47
	v_cvt_pk_bf16_f32 v32, v32, v33
	v_cvt_pk_bf16_f32 v33, v34, v35
	ds_write2_b64 v19, v[10:11], v[36:37] offset0:64 offset1:66
	ds_write2_b64 v19, v[14:15], v[24:25] offset0:72 offset1:74
	ds_write2_b64 v19, v[26:27], v[30:31] offset0:68 offset1:70
	ds_write2_b64 v19, v[28:29], v[32:33] offset0:76 offset1:78
	v_lshl_add_u64 v[10:11], v[64:65], 0, v[12:13]
	global_load_dwordx4 v[10:13], v[10:11], off nt
	s_waitcnt lgkmcnt(0)
	ds_read_b128 v[24:27], v55 offset:4608
	v_lshl_add_u64 v[14:15], s[24:25], 0, v[2:3]
	v_lshl_add_u64 v[28:29], v[14:15], 0, s[20:21]
	v_lshl_add_u64 v[30:31], v[28:29], 0, v[16:17]
	v_lshl_add_u64 v[4:5], v[28:29], 0, v[4:5]
	s_waitcnt lgkmcnt(0)
	v_lshlrev_b32_e32 v14, 16, v24
	v_and_b32_e32 v15, 0xffff0000, v24
	v_lshlrev_b32_e32 v16, 16, v25
	v_and_b32_e32 v17, 0xffff0000, v25
	v_lshlrev_b32_e32 v24, 16, v26
	v_and_b32_e32 v25, 0xffff0000, v26
	v_lshlrev_b32_e32 v26, 16, v27
	v_and_b32_e32 v27, 0xffff0000, v27
	v_lshl_add_u64 v[8:9], v[28:29], 0, v[8:9]
	s_waitcnt vmcnt(3)
	v_lshlrev_b32_e32 v32, 16, v56
	v_and_b32_e32 v33, 0xffff0000, v56
	v_lshlrev_b32_e32 v34, 16, v57
	v_and_b32_e32 v35, 0xffff0000, v57
	v_lshlrev_b32_e32 v36, 16, v58
	v_and_b32_e32 v37, 0xffff0000, v58
	v_lshlrev_b32_e32 v38, 16, v59
	v_and_b32_e32 v39, 0xffff0000, v59
	v_pk_mul_f32 v[14:15], v[32:33], v[14:15]
	v_pk_mul_f32 v[16:17], v[34:35], v[16:17]
	v_pk_mul_f32 v[24:25], v[36:37], v[24:25]
	v_pk_mul_f32 v[26:27], v[38:39], v[26:27]
	v_cvt_pk_bf16_f32 v14, v14, v15
	v_cvt_pk_bf16_f32 v15, v16, v17
	v_cvt_pk_bf16_f32 v16, v24, v25
	v_cvt_pk_bf16_f32 v17, v26, v27
	global_store_dwordx4 v[30:31], v[14:17], off sc0 sc1
	s_nop 1
	ds_read_b128 v[14:17], v55 offset:5760
	s_waitcnt vmcnt(2)
	v_lshlrev_b32_e32 v24, 16, v61
	v_and_b32_e32 v25, 0xffff0000, v61
	v_lshlrev_b32_e32 v26, 16, v62
	v_and_b32_e32 v27, 0xffff0000, v62
	s_waitcnt lgkmcnt(0)
	v_lshlrev_b32_e32 v30, 16, v14
	v_and_b32_e32 v31, 0xffff0000, v14
	v_lshlrev_b32_e32 v14, 16, v15
	v_and_b32_e32 v15, 0xffff0000, v15
	v_lshlrev_b32_e32 v32, 16, v16
	v_and_b32_e32 v33, 0xffff0000, v16
	v_pk_mul_f32 v[24:25], v[24:25], v[14:15]
	v_lshlrev_b32_e32 v40, 16, v60
	v_cvt_pk_bf16_f32 v15, v24, v25
	v_pk_mul_f32 v[24:25], v[26:27], v[32:33]
	v_and_b32_e32 v41, 0xffff0000, v60
	v_cvt_pk_bf16_f32 v16, v24, v25
	v_lshlrev_b32_e32 v24, 16, v17
	v_and_b32_e32 v25, 0xffff0000, v17
	v_lshlrev_b32_e32 v26, 16, v63
	v_and_b32_e32 v27, 0xffff0000, v63
	v_pk_mul_f32 v[30:31], v[40:41], v[30:31]
	v_pk_mul_f32 v[24:25], v[26:27], v[24:25]
	v_cvt_pk_bf16_f32 v14, v30, v31
	v_cvt_pk_bf16_f32 v17, v24, v25
	global_store_dwordx4 v[4:5], v[14:17], off sc0 sc1
	s_nop 1
	ds_read_b128 v[14:17], v55 offset:6912
	s_waitcnt vmcnt(1)
	v_lshlrev_b32_e32 v24, 16, v20
	v_and_b32_e32 v25, 0xffff0000, v20
	v_lshlrev_b32_e32 v20, 16, v21
	v_and_b32_e32 v21, 0xffff0000, v21
	s_waitcnt lgkmcnt(0)
	v_lshlrev_b32_e32 v4, 16, v14
	v_and_b32_e32 v5, 0xffff0000, v14
	v_pk_mul_f32 v[4:5], v[24:25], v[4:5]
	s_nop 0
	v_cvt_pk_bf16_f32 v14, v4, v5
	v_lshlrev_b32_e32 v4, 16, v15
	v_and_b32_e32 v5, 0xffff0000, v15
	v_pk_mul_f32 v[4:5], v[20:21], v[4:5]
	v_lshlrev_b32_e32 v20, 16, v22
	v_cvt_pk_bf16_f32 v15, v4, v5
	v_lshlrev_b32_e32 v4, 16, v16
	v_and_b32_e32 v5, 0xffff0000, v16
	v_and_b32_e32 v21, 0xffff0000, v22
	v_pk_mul_f32 v[4:5], v[20:21], v[4:5]
	v_lshlrev_b32_e32 v20, 16, v23
	v_cvt_pk_bf16_f32 v16, v4, v5
	v_lshlrev_b32_e32 v4, 16, v17
	v_and_b32_e32 v5, 0xffff0000, v17
	v_and_b32_e32 v21, 0xffff0000, v23
	v_pk_mul_f32 v[4:5], v[20:21], v[4:5]
	s_nop 0
	v_cvt_pk_bf16_f32 v17, v4, v5
	v_lshl_add_u64 v[4:5], v[28:29], 0, v[6:7]
	global_store_dwordx4 v[4:5], v[14:17], off sc0 sc1
	s_nop 1
	ds_read_b128 v[4:7], v55 offset:8064
	s_waitcnt vmcnt(0)
	v_lshlrev_b32_e32 v16, 16, v10
	v_and_b32_e32 v17, 0xffff0000, v10
	v_lshlrev_b32_e32 v10, 16, v11
	v_and_b32_e32 v11, 0xffff0000, v11
	s_waitcnt lgkmcnt(0)
	v_lshlrev_b32_e32 v14, 16, v4
	v_and_b32_e32 v15, 0xffff0000, v4
	v_pk_mul_f32 v[14:15], v[16:17], v[14:15]
	s_nop 0
	v_cvt_pk_bf16_f32 v4, v14, v15
	v_lshlrev_b32_e32 v14, 16, v5
	v_and_b32_e32 v15, 0xffff0000, v5
	v_pk_mul_f32 v[10:11], v[10:11], v[14:15]
	v_lshlrev_b32_e32 v14, 16, v12
	v_cvt_pk_bf16_f32 v5, v10, v11
	v_lshlrev_b32_e32 v10, 16, v6
	v_and_b32_e32 v11, 0xffff0000, v6
	v_and_b32_e32 v15, 0xffff0000, v12
	v_pk_mul_f32 v[10:11], v[14:15], v[10:11]
	v_lshlrev_b32_e32 v12, 16, v13
	v_cvt_pk_bf16_f32 v6, v10, v11
	v_lshlrev_b32_e32 v10, 16, v7
	v_and_b32_e32 v11, 0xffff0000, v7
	v_and_b32_e32 v13, 0xffff0000, v13
	v_pk_mul_f32 v[10:11], v[12:13], v[10:11]
	s_nop 0
	v_cvt_pk_bf16_f32 v7, v10, v11
	global_store_dwordx4 v[8:9], v[4:7], off sc0 sc1
	s_nop 1

.LBB0_536:
	s_lshl_b32 s68, s25, 6
	s_cmp_lt_i32 s73, 1
	v_and_b32_e32 v188, 31, v186
	s_cbranch_scc1 .LBB0_549
	s_and_b64 s[42:43], s[8:9], exec
	s_cselect_b32 s37, s64, 0x9700000
	v_add_u32_e32 v2, s24, v188
	s_waitcnt lgkmcnt(0)
	s_add_u32 s42, s26, s37
	v_ashrrev_i32_e32 v19, 5, v186
	s_addc_u32 s43, s27, 0
	v_lshlrev_b64 v[4:5], 10, v[2:3]
	v_lshl_add_u64 v[4:5], s[42:43], 0, v[4:5]
	s_lshl_b32 s42, s68, 1
	s_mov_b32 s43, s36
	v_lshlrev_b32_e32 v6, 3, v19
	v_lshl_add_u64 v[4:5], v[4:5], 0, s[42:43]
	v_ashrrev_i32_e32 v7, 31, v6
	s_and_b64 s[42:43], s[14:15], exec
	v_lshl_add_u64 v[20:21], v[6:7], 1, v[4:5]
	s_cselect_b32 s42, 0, 0x8000
	s_mov_b32 s43, s36
	v_lshl_add_u64 v[22:23], v[20:21], 0, s[42:43]
	global_load_dwordx4 v[4:7], v[22:23], off offset:96 nt
	global_load_dwordx4 v[8:11], v[22:23], off offset:64 nt
	global_load_dwordx4 v[12:15], v[20:21], off offset:96 nt
	global_load_dwordx4 v[132:135], v[20:21], off offset:64 nt
	global_load_dwordx4 v[136:139], v[22:23], off offset:32 nt
	global_load_dwordx4 v[140:143], v[22:23], off nt
	global_load_dwordx4 v[144:147], v[20:21], off offset:32 nt
	global_load_dwordx4 v[148:151], v[20:21], off nt
	s_andn2_b64 vcc, exec, s[40:41]
	s_mov_b64 s[40:41], -1
	s_cbranch_vccnz .LBB0_539
	s_waitcnt vmcnt(0)
	s_mov_b64 s[40:41], 0

.LBB0_576:
	s_mov_b32 s25, s36
	s_waitcnt lgkmcnt(0)
	s_add_u32 s28, s26, s14
	s_addc_u32 s29, s27, s15
	s_lshl_b64 s[14:15], s[24:25], 10
	s_add_u32 s14, s28, s14
	s_addc_u32 s15, s29, s15
	s_lshl_b32 s28, s68, 1
	s_add_u32 s14, s14, s28
	v_ashrrev_i32_e32 v16, 3, v186
	v_and_b32_e32 v87, 7, v186
	s_addc_u32 s15, s15, 0
	v_lshlrev_b32_e32 v2, 4, v87
	v_ashrrev_i32_e32 v17, 31, v16
	v_lshl_add_u64 v[88:89], s[14:15], 0, v[2:3]
	v_lshlrev_b64 v[10:11], 10, v[16:17]
	v_lshl_add_u64 v[6:7], v[88:89], 0, v[10:11]
	global_load_dwordx4 v[6:9], v[6:7], off nt
	v_mov_b32_e32 v5, s63
	v_ashrrev_i32_e32 v12, 2, v186
	v_mad_u32_u24 v5, v188, s67, v5
	v_and_b32_e32 v12, -8, v12
	v_add_u32_e32 v86, v5, v12
	v_pk_mul_f32 v[12:13], v[52:53], v[4:5] op_sel_hi:[1,0]
	v_pk_mul_f32 v[14:15], v[54:55], v[4:5] op_sel_hi:[1,0]
	v_cvt_pk_bf16_f32 v12, v12, v13
	v_cvt_pk_bf16_f32 v13, v14, v15
	v_pk_mul_f32 v[14:15], v[68:69], v[4:5] op_sel_hi:[1,0]
	v_add_u32_e32 v90, 8, v16
	v_cvt_pk_bf16_f32 v52, v14, v15
	v_pk_mul_f32 v[14:15], v[70:71], v[4:5] op_sel_hi:[1,0]
	v_ashrrev_i32_e32 v91, 31, v90
	v_cvt_pk_bf16_f32 v53, v14, v15
	v_pk_mul_f32 v[14:15], v[56:57], v[4:5] op_sel_hi:[1,0]
	v_pk_mul_f32 v[68:69], v[58:59], v[4:5] op_sel_hi:[1,0]
	v_cvt_pk_bf16_f32 v54, v14, v15
	v_lshlrev_b64 v[14:15], 10, v[90:91]
	v_lshl_add_u64 v[56:57], v[88:89], 0, v[14:15]
	global_load_dwordx4 v[56:59], v[56:57], off nt
	v_cvt_pk_bf16_f32 v55, v68, v69
	ds_write2_b64 v86, v[12:13], v[54:55] offset1:2
	v_pk_mul_f32 v[12:13], v[72:73], v[4:5] op_sel_hi:[1,0]
	v_pk_mul_f32 v[54:55], v[74:75], v[4:5] op_sel_hi:[1,0]
	v_cvt_pk_bf16_f32 v12, v12, v13
	v_cvt_pk_bf16_f32 v13, v54, v55
	ds_write2_b64 v86, v[52:53], v[12:13] offset0:8 offset1:10
	v_pk_mul_f32 v[12:13], v[60:61], v[4:5] op_sel_hi:[1,0]
	v_pk_mul_f32 v[52:53], v[62:63], v[4:5] op_sel_hi:[1,0]
	v_cvt_pk_bf16_f32 v12, v12, v13
	v_cvt_pk_bf16_f32 v13, v52, v53
	v_pk_mul_f32 v[52:53], v[76:77], v[4:5] op_sel_hi:[1,0]
	v_pk_mul_f32 v[54:55], v[78:79], v[4:5] op_sel_hi:[1,0]
	v_cvt_pk_bf16_f32 v52, v52, v53
	v_cvt_pk_bf16_f32 v53, v54, v55
	v_pk_mul_f32 v[54:55], v[64:65], v[4:5] op_sel_hi:[1,0]
	v_pk_mul_f32 v[60:61], v[66:67], v[4:5] op_sel_hi:[1,0]
	v_cvt_pk_bf16_f32 v54, v54, v55
	v_cvt_pk_bf16_f32 v55, v60, v61
	ds_write2_b64 v86, v[12:13], v[54:55] offset0:4 offset1:6
	v_pk_mul_f32 v[12:13], v[80:81], v[4:5] op_sel_hi:[1,0]
	v_pk_mul_f32 v[4:5], v[82:83], v[4:5] op_sel_hi:[1,0]
	v_add_u32_e32 v72, 16, v16
	v_cvt_pk_bf16_f32 v12, v12, v13
	v_cvt_pk_bf16_f32 v13, v4, v5
	v_ashrrev_i32_e32 v73, 31, v72
	ds_write2_b64 v86, v[52:53], v[12:13] offset0:12 offset1:14
	v_lshlrev_b64 v[52:53], 10, v[72:73]
	v_lshl_add_u64 v[4:5], v[88:89], 0, v[52:53]
	global_load_dwordx4 v[60:63], v[4:5], off nt
	v_add_u32_e32 v74, 24, v16
	v_ashrrev_i32_e32 v75, 31, v74
	v_lshlrev_b64 v[12:13], 10, v[74:75]
	v_lshl_add_u64 v[4:5], v[88:89], 0, v[12:13]
	global_load_dwordx4 v[64:67], v[4:5], off nt
	s_waitcnt lgkmcnt(0)
	v_add_u32_e32 v4, s63, v2
	v_mul_lo_u32 v5, v16, s67
	v_add_u32_e32 v55, v4, v5
	s_lshl_b64 s[24:25], s[24:25], 11
	ds_read_b128 v[68:71], v55
	s_add_u32 s24, s26, s24
	s_addc_u32 s25, s27, s25
	s_lshl_b32 s26, s30, 1
	s_add_u32 s24, s24, s26
	s_addc_u32 s25, s25, 0
	s_add_u32 s24, s24, s28
	s_waitcnt lgkmcnt(0)
	v_lshlrev_b32_e32 v4, 16, v68
	v_and_b32_e32 v5, 0xffff0000, v68
	v_lshlrev_b32_e32 v68, 16, v69
	v_and_b32_e32 v69, 0xffff0000, v69
	s_addc_u32 s25, s25, 0
	s_add_u32 s24, s24, 0x5400000
	s_addc_u32 s25, s25, 0
	v_lshl_add_u64 v[76:77], s[24:25], 0, v[2:3]
	v_lshlrev_b64 v[16:17], 11, v[16:17]
	s_and_b64 vcc, exec, s[6:7]
	s_waitcnt vmcnt(3)
	v_lshlrev_b32_e32 v78, 16, v6
	v_and_b32_e32 v79, 0xffff0000, v6
	v_lshlrev_b32_e32 v6, 16, v7
	v_and_b32_e32 v7, 0xffff0000, v7
	v_pk_mul_f32 v[4:5], v[78:79], v[4:5]
	v_pk_mul_f32 v[6:7], v[6:7], v[68:69]
	v_cvt_pk_bf16_f32 v4, v4, v5
	v_cvt_pk_bf16_f32 v5, v6, v7
	v_lshlrev_b32_e32 v6, 16, v70
	v_and_b32_e32 v7, 0xffff0000, v70
	v_lshlrev_b32_e32 v68, 16, v8
	v_and_b32_e32 v69, 0xffff0000, v8
	v_pk_mul_f32 v[6:7], v[68:69], v[6:7]
	v_lshlrev_b32_e32 v68, 16, v71
	v_and_b32_e32 v69, 0xffff0000, v71
	v_lshlrev_b32_e32 v8, 16, v9
	v_and_b32_e32 v9, 0xffff0000, v9
	v_pk_mul_f32 v[8:9], v[8:9], v[68:69]
	v_cvt_pk_bf16_f32 v6, v6, v7
	v_cvt_pk_bf16_f32 v7, v8, v9
	v_lshl_add_u64 v[8:9], v[76:77], 0, v[16:17]
	global_store_dwordx4 v[8:9], v[4:7], off sc0 sc1
	s_nop 1
	ds_read_b128 v[4:7], v55 offset:1152
	s_waitcnt vmcnt(2)
	v_lshlrev_b32_e32 v68, 16, v56
	v_and_b32_e32 v69, 0xffff0000, v56
	s_waitcnt lgkmcnt(0)
	v_lshlrev_b32_e32 v8, 16, v4
	v_and_b32_e32 v9, 0xffff0000, v4
	v_pk_mul_f32 v[8:9], v[68:69], v[8:9]
	v_lshlrev_b32_e32 v4, 16, v5
	v_cvt_pk_bf16_f32 v56, v8, v9
	v_and_b32_e32 v5, 0xffff0000, v5
	v_lshlrev_b32_e32 v8, 16, v57
	v_and_b32_e32 v9, 0xffff0000, v57
	v_pk_mul_f32 v[4:5], v[8:9], v[4:5]
	v_lshlrev_b32_e32 v8, 16, v58
	v_cvt_pk_bf16_f32 v57, v4, v5
	v_lshlrev_b32_e32 v4, 16, v6
	v_and_b32_e32 v5, 0xffff0000, v6
	v_and_b32_e32 v9, 0xffff0000, v58
	v_pk_mul_f32 v[4:5], v[8:9], v[4:5]
	v_lshlrev_b32_e32 v6, 16, v59
	v_cvt_pk_bf16_f32 v58, v4, v5
	v_lshlrev_b32_e32 v4, 16, v7
	v_and_b32_e32 v5, 0xffff0000, v7
	v_and_b32_e32 v7, 0xffff0000, v59
	v_pk_mul_f32 v[4:5], v[6:7], v[4:5]
	s_nop 0
	v_cvt_pk_bf16_f32 v59, v4, v5
	v_lshlrev_b64 v[4:5], 11, v[90:91]
	v_lshl_add_u64 v[6:7], v[76:77], 0, v[4:5]
	global_store_dwordx4 v[6:7], v[56:59], off sc0 sc1
	s_nop 1
	ds_read_b128 v[6:9], v55 offset:2304
	s_waitcnt vmcnt(1)
	v_lshlrev_b32_e32 v58, 16, v60
	v_and_b32_e32 v59, 0xffff0000, v60
	s_waitcnt vmcnt(0)
	v_lshlrev_b32_e32 v60, 16, v64
	s_waitcnt lgkmcnt(0)
	v_lshlrev_b32_e32 v56, 16, v6
	v_and_b32_e32 v57, 0xffff0000, v6
	v_pk_mul_f32 v[56:57], v[58:59], v[56:57]
	v_lshlrev_b32_e32 v6, 16, v7
	v_and_b32_e32 v7, 0xffff0000, v7
	v_lshlrev_b32_e32 v58, 16, v61
	v_and_b32_e32 v59, 0xffff0000, v61
	v_pk_mul_f32 v[6:7], v[58:59], v[6:7]
	v_cvt_pk_bf16_f32 v56, v56, v57
	v_cvt_pk_bf16_f32 v57, v6, v7
	v_lshlrev_b32_e32 v6, 16, v8
	v_and_b32_e32 v7, 0xffff0000, v8
	v_lshlrev_b32_e32 v58, 16, v62
	v_and_b32_e32 v59, 0xffff0000, v62
	v_pk_mul_f32 v[6:7], v[58:59], v[6:7]
	v_lshlrev_b32_e32 v8, 16, v63
	v_cvt_pk_bf16_f32 v58, v6, v7
	v_lshlrev_b32_e32 v6, 16, v9
	v_and_b32_e32 v7, 0xffff0000, v9
	v_and_b32_e32 v9, 0xffff0000, v63
	v_pk_mul_f32 v[6:7], v[8:9], v[6:7]
	v_and_b32_e32 v61, 0xffff0000, v64
	v_cvt_pk_bf16_f32 v59, v6, v7
	v_lshlrev_b64 v[6:7], 11, v[72:73]
	v_lshl_add_u64 v[8:9], v[76:77], 0, v[6:7]
	global_store_dwordx4 v[8:9], v[56:59], off sc0 sc1
	s_nop 1
	ds_read_b128 v[56:59], v55 offset:3456
	s_waitcnt lgkmcnt(0)
	v_lshlrev_b32_e32 v8, 16, v56
	v_and_b32_e32 v9, 0xffff0000, v56
	v_pk_mul_f32 v[8:9], v[60:61], v[8:9]
	v_lshlrev_b32_e32 v60, 16, v65
	v_cvt_pk_bf16_f32 v56, v8, v9
	v_lshlrev_b32_e32 v8, 16, v57
	v_and_b32_e32 v9, 0xffff0000, v57
	v_and_b32_e32 v61, 0xffff0000, v65
	v_pk_mul_f32 v[8:9], v[60:61], v[8:9]
	v_lshlrev_b32_e32 v60, 16, v66
	v_cvt_pk_bf16_f32 v57, v8, v9
	v_lshlrev_b32_e32 v8, 16, v58
	v_and_b32_e32 v9, 0xffff0000, v58
	v_and_b32_e32 v61, 0xffff0000, v66
	v_pk_mul_f32 v[8:9], v[60:61], v[8:9]
	v_lshlrev_b32_e32 v60, 16, v67
	v_cvt_pk_bf16_f32 v58, v8, v9
	v_lshlrev_b32_e32 v8, 16, v59
	v_and_b32_e32 v9, 0xffff0000, v59
	v_and_b32_e32 v61, 0xffff0000, v67
	v_pk_mul_f32 v[8:9], v[60:61], v[8:9]
	s_nop 0
	v_cvt_pk_bf16_f32 v59, v8, v9
	v_lshlrev_b64 v[8:9], 11, v[74:75]
	v_lshl_add_u64 v[60:61], v[76:77], 0, v[8:9]
	global_store_dwordx4 v[60:61], v[56:59], off sc0 sc1
	s_nop 1
	s_cbranch_vccnz .LBB0_500
	s_and_b64 vcc, exec, s[8:9]
	s_mov_b64 s[6:7], -1
	s_cbranch_vccnz .LBB0_579
	v_max_f32_e32 v2, v85, v85
	v_max_f32_e32 v54, v19, v19
	v_max_f32_e32 v2, v54, v2
	v_sub_f32_e32 v19, v19, v2
	v_sub_f32_e32 v2, v85, v2
	v_exp_f32_e32 v19, v19
	v_exp_f32_e32 v2, v2
	s_nop 0
	v_fmac_f32_e32 v2, v84, v19
	v_div_scale_f32 v54, s[6:7], v2, v2, v19
	v_rcp_f32_e32 v56, v54
	v_div_scale_f32 v57, vcc, v19, v2, v19
	s_mov_b64 s[6:7], 0
	v_fma_f32 v58, -v54, v56, 1.0
	v_fmac_f32_e32 v56, v58, v56
	v_mul_f32_e32 v58, v57, v56
	v_fma_f32 v59, -v54, v58, v57
	v_fmac_f32_e32 v58, v59, v56
	v_fma_f32 v54, -v54, v58, v57
	v_div_fmas_f32 v54, v54, v56, v58
	v_div_fixup_f32 v54, v54, v2, v19

.LBB0_720:
	s_add_u32 s44, s10, s14
	s_cmp_gt_i32 s37, 0
	s_cselect_b64 s[6:7], -1, 0
	s_cmp_lt_i32 s37, 1
	s_cbranch_scc1 .LBB0_722
	s_add_u32 s26, s10, s14
	s_addc_u32 s27, s11, s15
	s_add_i32 s28, s44, 0xffff8000
	s_cmp_lt_i32 s44, 0x8000
	s_cselect_b32 s26, s26, s28
	s_cselect_b32 s28, 0, 8
	s_cselect_b32 s27, s27, 0
	s_add_u32 s28, s8, s28
	s_load_dwordx2 s[24:25], s[8:9], 0xc0
	s_addc_u32 s29, s9, 0
	s_load_dwordx2 s[28:29], s[28:29], 0x0
	s_waitcnt vmcnt(0) lgkmcnt(0)
	v_lshl_add_u64 v[18:19], s[24:25], 0, v[84:85]
	s_lshl_b64 s[24:25], s[26:27], 12
	s_add_u32 s24, s28, s24
	s_addc_u32 s25, s29, s25
	v_lshl_add_u64 v[122:123], v[82:83], 4, s[24:25]
	global_load_dwordx2 v[92:93], v[18:19], off offset:-1536 nt
	global_load_dwordx2 v[90:91], v[18:19], off offset:-1024 nt
	global_load_dwordx2 v[88:89], v[18:19], off offset:-512 nt
	global_load_dwordx2 v[86:87], v[18:19], off nt
	global_load_dwordx4 v[30:33], v[122:123], off nt
	global_load_dwordx4 v[26:29], v[122:123], off offset:1024 nt
	global_load_dwordx4 v[22:25], v[122:123], off offset:2048 nt
	s_nop 0
	global_load_dwordx4 v[18:21], v[122:123], off offset:3072 nt
.LBB0_722:
	s_cmp_gt_i32 s37, 1
	s_cselect_b64 s[28:29], -1, 0
	s_cmp_lt_i32 s37, 2
	s_cbranch_scc1 .LBB0_731
	s_load_dwordx2 s[24:25], s[8:9], 0xc0
	s_add_i32 s26, s44, 1
	s_ashr_i32 s27, s26, 31
	s_lshl_b64 s[30:31], s[26:27], 11
	s_waitcnt lgkmcnt(0)
	s_add_u32 s24, s24, s30
	s_addc_u32 s25, s25, s31
	s_waitcnt vmcnt(0)
	v_lshl_add_u64 v[66:67], v[82:83], 3, s[24:25]
	s_add_i32 s24, s44, 0xffff8001
	s_cmpk_lt_i32 s44, 0x7fff
	s_cselect_b32 s24, s26, s24
	s_cselect_b32 s26, 0, 8
	s_cselect_b32 s25, s27, 0
	s_add_u32 s26, s8, s26
	s_addc_u32 s27, s9, 0
	s_load_dwordx2 s[26:27], s[26:27], 0x0
	s_lshl_b64 s[24:25], s[24:25], 12
	v_lshl_add_u64 v[68:69], v[66:67], 0, s[16:17]
	v_add_co_u32_e32 v66, vcc, s38, v66
	s_waitcnt lgkmcnt(0)
	s_add_u32 s24, s26, s24
	s_addc_u32 s25, s27, s25
	v_addc_co_u32_e32 v67, vcc, 0, v67, vcc
	v_lshl_add_u64 v[122:123], v[82:83], 4, s[24:25]
	global_load_dwordx2 v[116:117], v[66:67], off nt
	global_load_dwordx2 v[114:115], v[68:69], off offset:512 nt
	global_load_dwordx2 v[112:113], v[68:69], off offset:1024 nt
	global_load_dwordx2 v[110:111], v[68:69], off offset:1536 nt
	global_load_dwordx4 v[78:81], v[122:123], off nt
	global_load_dwordx4 v[74:77], v[122:123], off offset:1024 nt
	global_load_dwordx4 v[70:73], v[122:123], off offset:2048 nt
	s_nop 0
	global_load_dwordx4 v[66:69], v[122:123], off offset:3072 nt
	s_cmp_gt_i32 s37, 2
	s_cselect_b64 s[26:27], -1, 0
	s_cmp_lt_i32 s37, 3
	s_cbranch_scc0 .LBB0_732

.LBB0_725:
	s_load_dwordx2 s[30:31], s[8:9], 0xc0
	s_add_i32 s46, s44, 3
	s_ashr_i32 s47, s46, 31
	s_lshl_b64 s[48:49], s[46:47], 11
	s_waitcnt lgkmcnt(0)
	s_add_u32 s30, s30, s48
	s_addc_u32 s31, s31, s49
	s_waitcnt vmcnt(0)
	v_lshl_add_u64 v[34:35], v[82:83], 3, s[30:31]
	s_add_i32 s30, s44, 0xffff8003
	s_cmpk_lt_i32 s44, 0x7ffd
	s_cselect_b32 s45, 0, 8
	s_cselect_b32 s31, s47, 0
	s_cselect_b32 s30, s46, s30
	s_add_u32 s46, s8, s45
	s_addc_u32 s47, s9, 0
	s_load_dwordx2 s[46:47], s[46:47], 0x0
	s_lshl_b64 s[30:31], s[30:31], 12
	v_lshl_add_u64 v[36:37], v[34:35], 0, s[16:17]
	v_add_co_u32_e32 v34, vcc, s38, v34
	s_waitcnt lgkmcnt(0)
	s_add_u32 s30, s46, s30
	v_addc_co_u32_e32 v35, vcc, 0, v35, vcc
	s_addc_u32 s31, s47, s31
	global_load_dwordx2 v[100:101], v[34:35], off nt
	global_load_dwordx2 v[98:99], v[36:37], off offset:512 nt
	global_load_dwordx2 v[96:97], v[36:37], off offset:1024 nt
	global_load_dwordx2 v[94:95], v[36:37], off offset:1536 nt
	v_lshl_add_u64 v[34:35], v[82:83], 4, s[30:31]
	global_load_dwordx4 v[46:49], v[34:35], off nt
	global_load_dwordx4 v[42:45], v[34:35], off offset:1024 nt
	global_load_dwordx4 v[38:41], v[34:35], off offset:2048 nt
	s_nop 0
	global_load_dwordx4 v[34:37], v[34:35], off offset:3072 nt
	s_andn2_b64 vcc, exec, s[6:7]
	s_cbranch_vccz .LBB0_734

.LBB0_732:
	s_load_dwordx2 s[24:25], s[8:9], 0xc0
	s_add_i32 s30, s44, 2
	s_ashr_i32 s31, s30, 31
	s_lshl_b64 s[46:47], s[30:31], 11
	s_waitcnt lgkmcnt(0)
	s_add_u32 s24, s24, s46
	s_addc_u32 s25, s25, s47
	s_waitcnt vmcnt(0)
	v_lshl_add_u64 v[50:51], v[82:83], 3, s[24:25]
	s_add_i32 s24, s44, 0xffff8002
	s_cmpk_lt_i32 s44, 0x7ffe
	s_cselect_b32 s24, s30, s24
	s_cselect_b32 s30, 0, 8
	s_cselect_b32 s25, s31, 0
	s_add_u32 s30, s8, s30
	s_addc_u32 s31, s9, 0
	s_load_dwordx2 s[30:31], s[30:31], 0x0
	s_lshl_b64 s[24:25], s[24:25], 12
	v_lshl_add_u64 v[52:53], v[50:51], 0, s[16:17]
	v_add_co_u32_e32 v50, vcc, s38, v50
	s_waitcnt lgkmcnt(0)
	s_add_u32 s24, s30, s24
	s_addc_u32 s25, s31, s25
	v_addc_co_u32_e32 v51, vcc, 0, v51, vcc
	v_lshl_add_u64 v[122:123], v[82:83], 4, s[24:25]
	global_load_dwordx2 v[108:109], v[50:51], off nt
	global_load_dwordx2 v[106:107], v[52:53], off offset:512 nt
	global_load_dwordx2 v[104:105], v[52:53], off offset:1024 nt
	global_load_dwordx2 v[102:103], v[52:53], off offset:1536 nt
	global_load_dwordx4 v[62:65], v[122:123], off nt
	global_load_dwordx4 v[58:61], v[122:123], off offset:1024 nt
	global_load_dwordx4 v[54:57], v[122:123], off offset:2048 nt
	s_nop 0
	global_load_dwordx4 v[50:53], v[122:123], off offset:3072 nt
	s_cmp_gt_i32 s37, 3
	s_cselect_b64 s[24:25], -1, 0
	s_cmp_lt_i32 s37, 4
	s_cbranch_scc0 .LBB0_725

.LBB0_917:
	s_and_b64 s[26:27], s[68:69], exec
	s_cselect_b32 s25, 32, 0x800
	s_lshl_b32 s26, s24, 5
	s_add_i32 s28, s26, 0x8000
	s_lshl_b32 s29, s24, 11
	s_and_b64 s[26:27], s[68:69], exec
	s_cselect_b32 s26, s28, s29
	s_mul_i32 s27, s80, 0x8400
	s_ashr_i32 s28, s26, 31
	s_add_i32 s27, s27, s49
	s_add_u32 s26, s26, s27
	s_addc_u32 s27, s28, 0
	s_mov_b32 s37, 0
	s_cmp_ge_u32 s49, s25
	s_mul_i32 s28, s24, 3
	s_cbranch_scc1 .LBB0_923
	s_lshl_b64 s[30:31], s[26:27], 6
	v_lshl_add_u64 v[68:69], s[30:31], 0, v[106:107]
	v_lshlrev_b64 v[72:73], 1, v[68:69]
	v_lshl_add_u64 v[68:69], s[44:45], 0, v[72:73]
	v_lshl_add_u64 v[126:127], s[46:47], 0, v[72:73]
	global_load_ushort v95, v[68:69], off offset:128 nt
	global_load_ushort v89, v[68:69], off offset:384 nt
	global_load_ushort v83, v[68:69], off offset:640 nt
	global_load_ushort v77, v[68:69], off offset:896 nt
	global_load_ushort v80, v[68:69], off offset:768 nt
	global_load_ushort v92, v[68:69], off offset:512 nt
	global_load_ushort v101, v[68:69], off offset:256 nt
	global_load_ushort v124, v[68:69], off nt
	global_load_ushort v104, v[126:127], off offset:128 nt
	global_load_ushort v100, v[126:127], off offset:384 nt
	global_load_ushort v93, v[126:127], off offset:640 nt
	global_load_ushort v84, v[126:127], off offset:896 nt
	global_load_ushort v87, v[126:127], off offset:768 nt
	global_load_ushort v97, v[126:127], off offset:512 nt
	global_load_ushort v103, v[126:127], off offset:256 nt
	global_load_ushort v125, v[126:127], off nt
	global_load_ushort v85, v[68:69], off offset:1152 nt
	global_load_ushort v79, v[68:69], off offset:1408 nt
	global_load_ushort v73, v[68:69], off offset:1536 nt
	global_load_ushort v76, v[68:69], off offset:1664 nt
	global_load_ushort v67, v[68:69], off offset:1920 nt
	global_load_ushort v71, v[68:69], off offset:1792 nt
	global_load_ushort v96, v[68:69], off offset:1280 nt
	global_load_ushort v102, v[68:69], off offset:1024 nt
	global_load_ushort v99, v[126:127], off offset:1152 nt
	global_load_ushort v91, v[126:127], off offset:1408 nt
	global_load_ushort v81, v[126:127], off offset:1664 nt
	global_load_ushort v72, v[126:127], off offset:1920 nt
	global_load_ushort v75, v[126:127], off offset:1792 nt
	global_load_ushort v88, v[126:127], off offset:1536 nt
	global_load_ushort v98, v[126:127], off offset:1280 nt
	global_load_ushort v105, v[126:127], off offset:1024 nt
	s_andn2_b64 vcc, exec, s[42:43]
	s_mov_b64 s[30:31], -1
	s_cbranch_vccnz .LBB0_920
	global_load_ushort v126, v[68:69], off offset:-384 nt
	global_load_ushort v127, v[68:69], off offset:-256 nt
	s_nop 0
	global_load_ushort v68, v[68:69], off offset:-128 nt
	s_mov_b64 s[30:31], 0
	s_waitcnt vmcnt(2)
	v_lshlrev_b32_e32 v144, 16, v126
	s_waitcnt vmcnt(1)
	v_lshlrev_b32_e32 v161, 16, v127
	s_waitcnt vmcnt(0)
	v_lshlrev_b32_e32 v160, 16, v68

.LBB0_930:
	s_andn2_b64 vcc, exec, s[26:27]
	v_mov_b64_e32 v[160:161], v[156:157]
	s_cbranch_vccnz .LBB0_932
	v_add_co_u32_e32 v98, vcc, 0xfbe00000, v158
	s_nop 1
	v_addc_co_u32_e32 v99, vcc, -1, v159, vcc
	global_load_ushort v100, v[98:99], off offset:-2304 nt
	global_load_ushort v101, v[98:99], off offset:-1408 nt
	global_load_ushort v102, v[98:99], off offset:-1664 nt
	global_load_ushort v103, v[98:99], off offset:-1920 nt
	global_load_ushort v104, v[98:99], off offset:-2176 nt
	global_load_ushort v105, v[98:99], off offset:-2048 nt
	global_load_ushort v128, v[98:99], off offset:-1792 nt
	global_load_ushort v132, v[98:99], off offset:-1536 nt
	global_load_ushort v136, v[98:99], off offset:-1280 nt
	global_load_ushort v145, v[98:99], off offset:-384 nt
	global_load_ushort v150, v[98:99], off offset:-640 nt
	global_load_ushort v146, v[98:99], off offset:-896 nt
	global_load_ushort v140, v[98:99], off offset:-1152 nt
	global_load_ushort v147, v[98:99], off offset:-1024 nt
	global_load_ushort v151, v[98:99], off offset:-768 nt
	global_load_ushort v154, v[98:99], off offset:-512 nt
	global_load_ushort v155, v[98:99], off offset:-256 nt
	global_load_ushort v156, v[98:99], off offset:-128 nt
	s_nop 0
	global_load_ushort v98, v[98:99], off nt
	s_waitcnt vmcnt(18)
	v_lshlrev_b32_e32 v144, 16, v100
	s_waitcnt vmcnt(17)
	v_lshlrev_b32_e32 v137, 16, v101
	s_waitcnt vmcnt(16)
	v_lshlrev_b32_e32 v133, 16, v102
	s_waitcnt vmcnt(15)
	v_lshlrev_b32_e32 v129, 16, v103
	s_waitcnt vmcnt(14)
	v_lshlrev_b32_e32 v161, 16, v104
	s_waitcnt vmcnt(13)
	v_lshlrev_b32_e32 v160, 16, v105
	s_waitcnt vmcnt(12)
	v_lshlrev_b32_e32 v128, 16, v128
	s_waitcnt vmcnt(11)
	v_lshlrev_b32_e32 v132, 16, v132
	s_waitcnt vmcnt(10)
	v_lshlrev_b32_e32 v136, 16, v136
	s_waitcnt vmcnt(6)
	v_lshlrev_b32_e32 v141, 16, v140
	s_waitcnt vmcnt(5)
	v_lshlrev_b32_e32 v140, 16, v147
	v_lshlrev_b32_e32 v147, 16, v146
	s_waitcnt vmcnt(4)
	v_lshlrev_b32_e32 v146, 16, v151
	v_lshlrev_b32_e32 v151, 16, v150
	s_waitcnt vmcnt(3)
	v_lshlrev_b32_e32 v150, 16, v154
	s_waitcnt vmcnt(2)
	v_lshlrev_b32_e32 v155, 16, v155
	v_lshlrev_b32_e32 v154, 16, v145
	s_waitcnt vmcnt(1)
	v_lshlrev_b32_e32 v157, 16, v156
	s_waitcnt vmcnt(0)
	v_lshlrev_b32_e32 v156, 16, v98

.LBB0_934:
	s_and_b32 s54, s37, 0x400
	s_lshl_b32 s54, s54, 2
	s_add_i32 s54, s54, 0
	s_add_i32 s54, s54, 0x18000
	s_add_i32 s55, s54, s51
	v_lshlrev_b32_e32 v99, 2, v106
	v_add_u32_e32 v100, s55, v99
	ds_write2st64_b32 v100, v101, v98 offset1:1
	s_waitcnt lgkmcnt(0)
	v_add_u32_e32 v98, s54, v99
	s_waitcnt lgkmcnt(0)
	s_barrier
	ds_read2st64_b32 v[164:165], v98 offset1:1
	ds_read2st64_b32 v[168:169], v98 offset0:2 offset1:3
	ds_read2st64_b32 v[166:167], v98 offset0:4 offset1:5
	ds_read2st64_b32 v[162:163], v98 offset0:6 offset1:7
	ds_read2st64_b32 v[104:105], v98 offset0:8 offset1:9
	ds_read2st64_b32 v[102:103], v98 offset0:10 offset1:11
	ds_read2st64_b32 v[100:101], v98 offset0:12 offset1:13
	ds_read2st64_b32 v[98:99], v98 offset0:14 offset1:15
	s_andn2_b64 vcc, exec, s[28:29]
	s_waitcnt vmcnt(0) lgkmcnt(7)
	v_fmac_f32_e32 v165, v177, v164
	s_cbranch_vccnz .LBB0_937
	v_cndmask_b32_e64 v145, v165, v177, s[4:5]
	s_waitcnt lgkmcnt(6)
	v_fma_f32 v164, v168, v145, v169
	v_cndmask_b32_e64 v145, v145, v164, s[18:19]
	s_waitcnt lgkmcnt(5)
	v_fma_f32 v164, v166, v145, v167
	v_cndmask_b32_e64 v145, v145, v164, s[16:17]
	s_waitcnt lgkmcnt(4)
	v_fma_f32 v164, v162, v145, v163
	v_cndmask_b32_e64 v145, v145, v164, s[14:15]
	s_waitcnt lgkmcnt(3)
	v_fma_f32 v164, v104, v145, v105
	v_cndmask_b32_e64 v145, v145, v164, s[12:13]
	s_waitcnt lgkmcnt(2)
	v_fma_f32 v164, v102, v145, v103
	v_cndmask_b32_e64 v145, v145, v164, s[10:11]
	s_waitcnt lgkmcnt(1)
	v_fma_f32 v164, v100, v145, v101
	v_cndmask_b32_e64 v145, v145, v164, s[8:9]
	s_waitcnt lgkmcnt(0)
	v_fma_f32 v164, v98, v145, v99
	v_cndmask_b32_e64 v145, v145, v164, s[6:7]
	ds_read2st64_b32 v[178:179], v1 offset0:32 offset1:33
	ds_read2st64_b32 v[180:181], v1 offset0:16 offset1:17
	ds_read2st64_b32 v[182:183], v1 offset0:18 offset1:19
	ds_read2st64_b32 v[186:187], v1 offset0:20 offset1:21
	ds_read2st64_b32 v[188:189], v1 offset0:22 offset1:23
	ds_read2st64_b32 v[190:191], v1 offset0:34 offset1:35
	ds_read2st64_b32 v[192:193], v1 offset0:36 offset1:37
	ds_read2st64_b32 v[194:195], v1 offset0:38 offset1:39
	s_waitcnt lgkmcnt(6)
	v_fma_f32 v145, v145, v180, v178
	v_fmac_f32_e32 v179, v145, v181
	v_mul_f32_e32 v164, v125, v145
	v_add_co_u32_e32 v196, vcc, s77, v158
	v_mul_f32_e32 v145, v124, v179
	s_nop 0
	v_addc_co_u32_e32 v197, vcc, -1, v159, vcc
	v_cvt_pk_bf16_f32 v145, v145, s0
	global_store_short v[196:197], v145, off offset:-1792
	s_waitcnt lgkmcnt(2)
	v_fma_f32 v145, v179, v182, v190
	v_cvt_pk_bf16_f32 v164, v164, s0
	v_fmac_f32_e32 v191, v145, v183
	global_store_short v[196:197], v164, off offset:-1920
	v_mul_f32_e32 v164, v127, v145
	v_mul_f32_e32 v145, v126, v191
	v_cvt_pk_bf16_f32 v145, v145, s0
	global_store_short v[196:197], v145, off offset:-1536
	s_waitcnt lgkmcnt(1)
	v_fma_f32 v145, v191, v186, v192
	v_cvt_pk_bf16_f32 v164, v164, s0
	v_fmac_f32_e32 v193, v145, v187
	global_store_short v[196:197], v164, off offset:-1664
	v_mul_f32_e32 v164, v131, v145
	v_mul_f32_e32 v145, v130, v193
	v_cvt_pk_bf16_f32 v145, v145, s0
	global_store_short v[196:197], v145, off offset:-1280
	s_waitcnt lgkmcnt(0)
	v_fma_f32 v145, v193, v188, v194
	v_cvt_pk_bf16_f32 v164, v164, s0
	v_fmac_f32_e32 v195, v145, v189
	global_store_short v[196:197], v164, off offset:-1408
	v_mul_f32_e32 v164, v135, v145
	v_mul_f32_e32 v145, v134, v195
	v_cvt_pk_bf16_f32 v164, v164, s0
	v_cvt_pk_bf16_f32 v145, v145, s0
	global_store_short v[196:197], v164, off offset:-1152
	global_store_short v[196:197], v145, off offset:-1024
	ds_read2st64_b32 v[178:179], v1 offset0:40 offset1:41
	ds_read2st64_b32 v[180:181], v1 offset0:24 offset1:25
	ds_read2st64_b32 v[182:183], v1 offset0:26 offset1:27
	ds_read2st64_b32 v[186:187], v1 offset0:28 offset1:29
	ds_read2st64_b32 v[188:189], v1 offset0:30 offset1:31
	ds_read2st64_b32 v[190:191], v1 offset0:42 offset1:43
	ds_read2st64_b32 v[192:193], v1 offset0:44 offset1:45
	ds_read2st64_b32 v[198:199], v1 offset0:46 offset1:47
	s_waitcnt lgkmcnt(6)
	v_fma_f32 v145, v195, v180, v178
	v_fmac_f32_e32 v179, v145, v181
	v_mul_f32_e32 v164, v139, v145
	v_mul_f32_e32 v145, v138, v179
	v_cvt_pk_bf16_f32 v145, v145, s0
	global_store_short v[196:197], v145, off offset:-768
	s_waitcnt lgkmcnt(2)
	v_fma_f32 v145, v179, v182, v190
	v_cvt_pk_bf16_f32 v164, v164, s0
	v_fmac_f32_e32 v191, v145, v183
	global_store_short v[196:197], v164, off offset:-896
	v_mul_f32_e32 v164, v143, v145
	v_mul_f32_e32 v145, v142, v191
	v_cvt_pk_bf16_f32 v145, v145, s0
	global_store_short v[196:197], v145, off offset:-512
	s_waitcnt lgkmcnt(1)
	v_fma_f32 v145, v191, v186, v192
	v_cvt_pk_bf16_f32 v164, v164, s0
	v_fmac_f32_e32 v193, v145, v187
	global_store_short v[196:197], v164, off offset:-640
	v_mul_f32_e32 v164, v149, v145
	v_mul_f32_e32 v145, v148, v193
	v_cvt_pk_bf16_f32 v145, v145, s0
	global_store_short v[196:197], v145, off offset:-256
	s_waitcnt lgkmcnt(0)
	v_fma_f32 v145, v193, v188, v198
	v_cvt_pk_bf16_f32 v164, v164, s0
	v_fmac_f32_e32 v199, v145, v189
	global_store_short v[196:197], v164, off offset:-384
	v_mul_f32_e32 v164, v153, v145
	v_mul_f32_e32 v145, v152, v199
	v_cvt_pk_bf16_f32 v164, v164, s0
	v_cvt_pk_bf16_f32 v145, v145, s0
	s_andn2_b64 vcc, exec, s[26:27]
	global_store_short v[196:197], v164, off offset:-128
	global_store_short v[196:197], v145, off
	s_cbranch_vccnz .LBB0_937
	global_load_ushort v134, v[158:159], off offset:-1152 nt
	global_load_ushort v130, v[158:159], off offset:-1408 nt
	global_load_ushort v126, v[158:159], off offset:-1664 nt
	global_load_ushort v124, v[158:159], off offset:-1920 nt
	global_load_ushort v127, v[158:159], off offset:-1792 nt
	global_load_ushort v131, v[158:159], off offset:-1536 nt
	global_load_ushort v135, v[158:159], off offset:-1280 nt
	global_load_ushort v138, v[158:159], off offset:-1024 nt
	global_load_ushort v145, v[158:159], off offset:-128 nt
	global_load_ushort v148, v[158:159], off offset:-384 nt
	global_load_ushort v142, v[158:159], off offset:-640 nt
	global_load_ushort v139, v[158:159], off offset:-896 nt
	global_load_ushort v143, v[158:159], off offset:-768 nt
	global_load_ushort v149, v[158:159], off offset:-512 nt
	global_load_ushort v152, v[158:159], off offset:-256 nt
	global_load_ushort v164, v[158:159], off nt
	s_waitcnt vmcnt(12)
	v_lshlrev_b32_e32 v125, 16, v124
	s_waitcnt vmcnt(11)
	v_lshlrev_b32_e32 v124, 16, v127
	v_lshlrev_b32_e32 v127, 16, v126
	s_waitcnt vmcnt(10)
	v_lshlrev_b32_e32 v126, 16, v131
	v_lshlrev_b32_e32 v131, 16, v130
	s_waitcnt vmcnt(9)
	v_lshlrev_b32_e32 v130, 16, v135
	v_lshlrev_b32_e32 v135, 16, v134
	s_waitcnt vmcnt(8)
	v_lshlrev_b32_e32 v134, 16, v138
	s_waitcnt vmcnt(4)
	v_lshlrev_b32_e32 v139, 16, v139
	s_waitcnt vmcnt(3)
	v_lshlrev_b32_e32 v138, 16, v143
	v_lshlrev_b32_e32 v143, 16, v142
	s_waitcnt vmcnt(2)
	v_lshlrev_b32_e32 v142, 16, v149
	v_lshlrev_b32_e32 v149, 16, v148
	s_waitcnt vmcnt(1)
	v_lshlrev_b32_e32 v148, 16, v152
	v_lshlrev_b32_e32 v153, 16, v145
	s_waitcnt vmcnt(0)
	v_lshlrev_b32_e32 v152, 16, v164

.LBB0_1081:
	s_cmp_gt_i32 s29, 0
	s_cselect_b64 s[2:3], -1, 0
	s_cmp_lt_i32 s29, 1
	s_cbranch_scc1 .LBB0_1083
	s_load_dwordx2 s[22:23], s[0:1], 0xc0
	s_waitcnt vmcnt(1) lgkmcnt(0)
	v_lshl_add_u64 v[46:47], s[22:23], 0, v[16:17]
	v_add_co_u32_e32 v94, vcc, 0xf7a00000, v46
	global_load_dwordx2 v[26:27], v[46:47], off offset:-1536 nt
	global_load_dwordx2 v[24:25], v[46:47], off offset:-1024 nt
	global_load_dwordx2 v[22:23], v[46:47], off offset:-512 nt
	global_load_dwordx2 v[20:21], v[46:47], off nt
	v_addc_co_u32_e32 v95, vcc, -1, v47, vcc
	global_load_dwordx2 v[52:53], v[94:95], off offset:-1536 nt
	global_load_dwordx2 v[50:51], v[94:95], off offset:-1024 nt
	global_load_dwordx2 v[48:49], v[94:95], off offset:-512 nt
	global_load_dwordx2 v[46:47], v[94:95], off nt
	s_add_u32 s22, s22, s5
	s_addc_u32 s23, s23, s28
	global_load_dword v76, v77, s[22:23]
.LBB0_1083:
	s_cmp_gt_i32 s29, 1
	s_cselect_b64 s[26:27], -1, 0
	s_cmp_lt_i32 s29, 2
	s_cbranch_scc1 .LBB0_1087
	s_load_dwordx2 s[22:23], s[0:1], 0xc0
	s_ashr_i32 s9, s8, 31
	s_lshl_b64 s[24:25], s[8:9], 11
	s_waitcnt lgkmcnt(0)
	s_add_u32 s24, s22, s24
	s_addc_u32 s25, s23, s25
	s_waitcnt vmcnt(1)
	v_lshl_add_u64 v[78:79], v[184:185], 3, s[24:25]
	v_add_co_u32_e32 v82, vcc, 0x9700000, v78
	v_lshl_add_u64 v[80:81], v[78:79], 0, s[6:7]
	s_nop 0
	v_addc_co_u32_e32 v83, vcc, 0, v79, vcc
	v_add_co_u32_e32 v96, vcc, 0x1100000, v78
	s_lshl_b64 s[24:25], s[8:9], 2
	s_nop 0
	v_addc_co_u32_e32 v97, vcc, 0, v79, vcc
	global_load_dwordx2 v[34:35], v[82:83], off nt
	global_load_dwordx2 v[32:33], v[80:81], off offset:512 nt
	global_load_dwordx2 v[30:31], v[80:81], off offset:1024 nt
	global_load_dwordx2 v[28:29], v[80:81], off offset:1536 nt
	v_lshl_add_u64 v[94:95], v[78:79], 0, s[10:11]
	global_load_dwordx2 v[84:85], v[96:97], off nt
	global_load_dwordx2 v[82:83], v[94:95], off offset:512 nt
	global_load_dwordx2 v[80:81], v[94:95], off offset:1024 nt
	global_load_dwordx2 v[78:79], v[94:95], off offset:1536 nt
	s_add_u32 s22, s22, s24
	s_addc_u32 s23, s23, s25
	global_load_dword v86, v87, s[22:23]
	s_cmp_gt_i32 s29, 2
	s_cselect_b64 s[24:25], -1, 0
	s_cmp_lt_i32 s29, 3
	s_cbranch_scc0 .LBB0_1088

.LBB0_1086:
	s_load_dwordx2 s[34:35], s[0:1], 0xc0
	s_add_i32 s36, s8, 2
	s_ashr_i32 s37, s36, 31
	s_lshl_b64 s[38:39], s[36:37], 11
	s_waitcnt lgkmcnt(0)
	s_add_u32 s38, s34, s38
	s_addc_u32 s39, s35, s39
	s_waitcnt vmcnt(7)
	v_lshl_add_u64 v[36:37], v[184:185], 3, s[38:39]
	s_waitcnt vmcnt(1)
	v_add_co_u32_e32 v40, vcc, 0x9700000, v36
	s_lshl_b64 s[36:37], s[36:37], 2
	s_nop 0
	v_addc_co_u32_e32 v41, vcc, 0, v37, vcc
	v_add_co_u32_e32 v44, vcc, 0x1100000, v36
	v_lshl_add_u64 v[94:95], v[36:37], 0, s[6:7]
	s_nop 0
	v_addc_co_u32_e32 v45, vcc, 0, v37, vcc
	v_lshl_add_u64 v[42:43], v[36:37], 0, s[10:11]
	global_load_dwordx2 v[60:61], v[44:45], off nt
	global_load_dwordx2 v[36:37], v[40:41], off nt
	global_load_dwordx2 v[66:67], v[42:43], off offset:512 nt
	global_load_dwordx2 v[64:65], v[42:43], off offset:1024 nt
	global_load_dwordx2 v[62:63], v[42:43], off offset:1536 nt
	s_add_u32 s34, s34, s36
	s_addc_u32 s35, s35, s37
	global_load_dwordx2 v[44:45], v[94:95], off offset:512 nt
	global_load_dwordx2 v[42:43], v[94:95], off offset:1024 nt
	global_load_dwordx2 v[40:41], v[94:95], off offset:1536 nt
	global_load_dword v88, v87, s[34:35]
	s_andn2_b64 vcc, exec, s[2:3]
	v_mbcnt_hi_u32_b32 v93, -1, v92
	s_cbranch_vccz .LBB0_1090
	s_branch .LBB0_1091

.LBB0_1088:
	s_load_dwordx2 s[22:23], s[0:1], 0xc0
	s_add_i32 s34, s8, 1
	s_ashr_i32 s35, s34, 31
	s_lshl_b64 s[36:37], s[34:35], 11
	s_waitcnt lgkmcnt(0)
	s_add_u32 s36, s22, s36
	s_addc_u32 s37, s23, s37
	s_waitcnt vmcnt(7)
	v_lshl_add_u64 v[38:39], v[184:185], 3, s[36:37]
	s_waitcnt vmcnt(1)
	v_add_co_u32_e32 v54, vcc, 0x9700000, v38
	s_lshl_b64 s[34:35], s[34:35], 2
	s_nop 0
	v_addc_co_u32_e32 v55, vcc, 0, v39, vcc
	v_add_co_u32_e32 v58, vcc, 0x1100000, v38
	v_lshl_add_u64 v[94:95], v[38:39], 0, s[6:7]
	s_nop 0
	v_addc_co_u32_e32 v59, vcc, 0, v39, vcc
	v_lshl_add_u64 v[56:57], v[38:39], 0, s[10:11]
	global_load_dwordx2 v[68:69], v[58:59], off nt
	global_load_dwordx2 v[38:39], v[54:55], off nt
	global_load_dwordx2 v[74:75], v[56:57], off offset:512 nt
	global_load_dwordx2 v[72:73], v[56:57], off offset:1024 nt
	global_load_dwordx2 v[70:71], v[56:57], off offset:1536 nt
	s_add_u32 s22, s22, s34
	s_addc_u32 s23, s23, s35
	global_load_dwordx2 v[58:59], v[94:95], off offset:512 nt
	global_load_dwordx2 v[56:57], v[94:95], off offset:1024 nt
	global_load_dwordx2 v[54:55], v[94:95], off offset:1536 nt
	global_load_dword v90, v87, s[22:23]
	s_cmp_gt_i32 s29, 3
	s_cselect_b64 s[22:23], -1, 0
	s_cmp_lt_i32 s29, 4
	s_cbranch_scc0 .LBB0_1086
